# P4 Q/KV GEMMs: full vmcnt(0) in the middle of each tile's first MMA segment removed (on v46)
# speedup vs baseline: 1.0058x; 1.0058x over previous
; #define PG8_STAGE(bufoff, gbase, voff) do { _Pragma("unroll") for (int _i = 0; _i < 2; ++_i) \
;         __builtin_amdgcn_global_load_lds((const unsigned*)((const char*)(gbase) + (voff)[_i]), (LAS unsigned*)(lds + (bufoff) + ldsw + _i * 8192), 16, 0, 0); } while (0)
; #define PG8_LDA(dst, b, h) do { _Pragma("unroll") for (int m = 0; m < 4; ++m) _Pragma("unroll") for (int k = 0; k < 2; ++k) dst[m][k] = *(const LAS bf16x8*)(lds + PG8_SA(b, h) + aoff + m * 2048 + k * 1024); } while (0)
; #define PG8_LDB(dst, b, h) do { _Pragma("unroll") for (int n = 0; n < 2; ++n) _Pragma("unroll") for (int k = 0; k < 2; ++k) dst[n][k] = *(const LAS bf16x8*)(lds + PG8_SB(b, h) + boff + n * 2048 + k * 1024); } while (0)
; #define PG8_MMA(ai, bj, At, Bt) do { __builtin_amdgcn_s_setprio(1); _Pragma("unroll") for (int m = 0; m < 4; ++m) _Pragma("unroll") for (int n = 0; n < 2; ++n) _Pragma("unroll") for (int k = 0; k < 2; ++k) \
;         acc[ai][bj][m][n] = __builtin_amdgcn_mfma_f32_16x16x32_bf16(Bt[n][k], At[m][k], acc[ai][bj][m][n], 0, 0, 0); __builtin_amdgcn_s_setprio(0); } while (0)
; #define PG8_WAIT_V(n) asm volatile("s_waitcnt vmcnt(" #n ")" ::: "memory")
; #define PG8_WAIT_L(n) asm volatile("s_waitcnt lgkmcnt(" #n ")" ::: "memory")
; #define PG8_BAR __builtin_amdgcn_s_barrier()
; #define PG8_SCHED __builtin_amdgcn_sched_barrier(0)
; template <class Epi, bool ALIGN_EPI, int K, int LDA, int LDB>
; __device__ __forceinline__ void gemm_phase(LAS unsigned char* lds, const int wid, const Gemm g, const StaticOrder& S, const Epi& E) {
;     ...
;             PG8_LDB(B0, 0, 0); PG8_LDB(B1, 0, 1); PG8_SCHED; PG8_LDA(At, 0, 0); PG8_STAGE(PG8_SA(1, 1), a1 + hA, voffA);
;             PG8_WAIT_V(8); PG8_WAIT_L(0); PG8_BAR; PG8_MMA(0, 0, At, B0); PG8_MMA(0, 1, At, B1); PG8_BAR; PG8_SCHED;
;             PG8_LDA(At, 0, 1); PG8_STAGE(PG8_SB(0, 0), b2, voffB); PG8_STAGE(PG8_SB(0, 1), b2 + hB, voffB); PG8_STAGE(PG8_SA(0, 0), a2, voffA);
;             PG8_WAIT_V(8); PG8_WAIT_L(0); PG8_BAR; PG8_MMA(1, 0, At, B0); PG8_MMA(1, 1, At, B1); PG8_BAR; PG8_SCHED;
.LBB0_665:
	ds_read_b128 v[8:11], v158
	ds_read_b128 v[12:15], v158 offset:1024
	ds_read_b128 v[16:19], v158 offset:2048
	ds_read_b128 v[20:23], v158 offset:3072
	ds_read_b128 v[24:27], v159
	ds_read_b128 v[28:31], v159 offset:1024
	ds_read_b128 v[32:35], v159 offset:2048
	ds_read_b128 v[36:39], v159 offset:3072
	s_add_u32 s6, s36, 0xa0080
	s_addc_u32 s7, s37, 0
	s_add_i32 s71, s42, 0xc000
	v_lshl_add_u64 v[64:65], s[6:7], 0, v[142:143]
	s_mov_b32 m0, s71
	ds_read_b128 v[0:3], v157
	ds_read_b128 v[4:7], v157 offset:1024
	ds_read_b128 v[40:43], v157 offset:2048
	ds_read_b128 v[44:47], v157 offset:3072
	ds_read_b128 v[48:51], v157 offset:4096
	ds_read_b128 v[52:55], v157 offset:5120
	ds_read_b128 v[56:59], v157 offset:6144
	ds_read_b128 v[60:63], v157 offset:7168
	global_load_lds_dwordx4 v[64:65], off
	v_lshl_add_u64 v[64:65], s[6:7], 0, v[138:139]
	s_add_i32 s6, s42, 0xe000
	s_mov_b32 m0, s6
	s_nop 0
	global_load_lds_dwordx4 v[64:65], off
	s_waitcnt vmcnt(8)
	s_waitcnt lgkmcnt(0)
	s_barrier
	s_setprio 1
	s_waitcnt lgkmcnt(0)
	v_mfma_f32_16x16x32_bf16 v[64:67], v[8:11], v[0:3], 0
	v_mfma_f32_16x16x32_bf16 v[68:71], v[16:19], v[0:3], 0
	v_mfma_f32_16x16x32_bf16 v[72:75], v[8:11], v[40:43], 0
	v_mfma_f32_16x16x32_bf16 v[76:79], v[16:19], v[40:43], 0
	v_mfma_f32_16x16x32_bf16 v[80:83], v[8:11], v[48:51], 0
	v_mfma_f32_16x16x32_bf16 v[84:87], v[16:19], v[48:51], 0
	v_mfma_f32_16x16x32_bf16 v[88:91], v[8:11], v[56:59], 0
	v_mfma_f32_16x16x32_bf16 v[92:95], v[16:19], v[56:59], 0
	v_mfma_f32_16x16x32_bf16 v[64:67], v[12:15], v[4:7], v[64:67]
	v_mfma_f32_16x16x32_bf16 v[68:71], v[20:23], v[4:7], v[68:71]
	v_mfma_f32_16x16x32_bf16 v[72:75], v[12:15], v[44:47], v[72:75]
	v_mfma_f32_16x16x32_bf16 v[76:79], v[20:23], v[44:47], v[76:79]
	v_mfma_f32_16x16x32_bf16 v[80:83], v[12:15], v[52:55], v[80:83]
	v_mfma_f32_16x16x32_bf16 v[84:87], v[20:23], v[52:55], v[84:87]
	v_mfma_f32_16x16x32_bf16 v[88:91], v[12:15], v[60:63], v[88:91]
	v_mfma_f32_16x16x32_bf16 v[92:95], v[20:23], v[60:63], v[92:95]
	v_mfma_f32_16x16x32_bf16 v[96:99], v[24:27], v[0:3], 0
	v_mfma_f32_16x16x32_bf16 v[0:3], v[32:35], v[0:3], 0
	v_mfma_f32_16x16x32_bf16 v[100:103], v[36:39], v[4:7], v[0:3]
	v_mfma_f32_16x16x32_bf16 v[0:3], v[24:27], v[40:43], 0
	v_mfma_f32_16x16x32_bf16 v[104:107], v[28:31], v[44:47], v[0:3]
	v_mfma_f32_16x16x32_bf16 v[0:3], v[32:35], v[40:43], 0
	v_mfma_f32_16x16x32_bf16 v[40:43], v[36:39], v[44:47], v[0:3]
	v_mfma_f32_16x16x32_bf16 v[0:3], v[24:27], v[48:51], 0
	v_mfma_f32_16x16x32_bf16 v[44:47], v[28:31], v[52:55], v[0:3]
	v_mfma_f32_16x16x32_bf16 v[0:3], v[32:35], v[48:51], 0
	v_mfma_f32_16x16x32_bf16 v[48:51], v[36:39], v[52:55], v[0:3]
	v_mfma_f32_16x16x32_bf16 v[0:3], v[24:27], v[56:59], 0
	v_mfma_f32_16x16x32_bf16 v[52:55], v[28:31], v[60:63], v[0:3]
	v_mfma_f32_16x16x32_bf16 v[0:3], v[32:35], v[56:59], 0
	v_mfma_f32_16x16x32_bf16 v[96:99], v[28:31], v[4:7], v[96:99]
	v_mfma_f32_16x16x32_bf16 v[56:59], v[36:39], v[60:63], v[0:3]
	s_setprio 0
	s_barrier
	s_nop 3
	v_lshl_add_u64 v[0:1], s[38:39], 0, v[140:141]
	s_add_i32 s68, s59, s0
	v_lshl_add_u64 v[2:3], v[0:1], 0, s[22:23]
	s_mov_b32 m0, s68
	s_add_i32 s7, s68, 0x2000
	ds_read_b128 v[60:63], v157 offset:16384
	ds_read_b128 v[108:111], v157 offset:17408
	ds_read_b128 v[112:115], v157 offset:18432
	ds_read_b128 v[116:119], v157 offset:19456
	ds_read_b128 v[120:123], v157 offset:20480
	ds_read_b128 v[124:127], v157 offset:21504
	ds_read_b128 v[128:131], v157 offset:22528
	ds_read_b128 v[132:135], v157 offset:23552
	global_load_lds_dwordx4 v[2:3], off
	v_lshl_add_u64 v[2:3], s[38:39], 0, v[136:137]
	s_add_u32 s72, s38, 0x18100
	v_lshl_add_u64 v[4:5], v[2:3], 0, s[22:23]
	s_mov_b32 m0, s7
	s_addc_u32 s73, s39, 0
	s_add_i32 s66, s60, s0
	global_load_lds_dwordx4 v[4:5], off
	v_lshl_add_u64 v[4:5], s[72:73], 0, v[140:141]
	s_mov_b32 m0, s66
	s_add_i32 s67, s66, 0x2000
	global_load_lds_dwordx4 v[4:5], off
	v_lshl_add_u64 v[4:5], s[72:73], 0, v[136:137]
	s_mov_b32 m0, s67
	s_nop 0
	global_load_lds_dwordx4 v[4:5], off
	v_lshl_add_u64 v[4:5], s[36:37], 0, v[142:143]
	v_lshl_add_u64 v[6:7], v[4:5], 0, s[22:23]
	s_mov_b32 m0, s42
	s_nop 0
	global_load_lds_dwordx4 v[6:7], off
	v_lshl_add_u64 v[6:7], s[36:37], 0, v[138:139]
	v_lshl_add_u64 v[148:149], v[6:7], 0, s[22:23]
	s_mov_b32 m0, s51
	s_nop 0
	global_load_lds_dwordx4 v[148:149], off
	s_waitcnt vmcnt(8)
	s_waitcnt lgkmcnt(0)
	s_barrier
	s_setprio 1
	s_waitcnt lgkmcnt(0)
	v_mfma_f32_16x16x32_bf16 v[148:151], v[8:11], v[60:63], 0
	v_mfma_f32_16x16x32_bf16 v[160:163], v[8:11], v[112:115], 0
	v_mfma_f32_16x16x32_bf16 v[168:171], v[8:11], v[120:123], 0
	v_mfma_f32_16x16x32_bf16 v[8:11], v[8:11], v[128:131], 0
	v_mfma_f32_16x16x32_bf16 v[148:151], v[12:15], v[108:111], v[148:151]
	v_mfma_f32_16x16x32_bf16 v[152:155], v[16:19], v[60:63], 0
	v_mfma_f32_16x16x32_bf16 v[160:163], v[12:15], v[116:119], v[160:163]
	v_mfma_f32_16x16x32_bf16 v[164:167], v[16:19], v[112:115], 0
	v_mfma_f32_16x16x32_bf16 v[168:171], v[12:15], v[124:127], v[168:171]
	v_mfma_f32_16x16x32_bf16 v[172:175], v[16:19], v[120:123], 0
	v_mfma_f32_16x16x32_bf16 v[10:13], v[12:15], v[132:135], v[8:11]
	v_mfma_f32_16x16x32_bf16 v[14:17], v[16:19], v[128:131], 0
	v_mfma_f32_16x16x32_bf16 v[14:17], v[20:23], v[132:135], v[14:17]
	v_mfma_f32_16x16x32_bf16 v[152:155], v[20:23], v[108:111], v[152:155]
	v_mfma_f32_16x16x32_bf16 v[164:167], v[20:23], v[116:119], v[164:167]
	v_mfma_f32_16x16x32_bf16 v[172:175], v[20:23], v[124:127], v[172:175]
	v_mfma_f32_16x16x32_bf16 v[18:21], v[24:27], v[60:63], 0
	v_mfma_f32_16x16x32_bf16 v[60:63], v[32:35], v[60:63], 0
	v_mfma_f32_16x16x32_bf16 v[18:21], v[28:31], v[108:111], v[18:21]
	v_mfma_f32_16x16x32_bf16 v[60:63], v[36:39], v[108:111], v[60:63]
	v_mfma_f32_16x16x32_bf16 v[108:111], v[24:27], v[112:115], 0
	v_mfma_f32_16x16x32_bf16 v[112:115], v[32:35], v[112:115], 0
	v_mfma_f32_16x16x32_bf16 v[108:111], v[28:31], v[116:119], v[108:111]
	v_mfma_f32_16x16x32_bf16 v[112:115], v[36:39], v[116:119], v[112:115]
	v_mfma_f32_16x16x32_bf16 v[116:119], v[24:27], v[120:123], 0
	v_mfma_f32_16x16x32_bf16 v[22:25], v[24:27], v[128:131], 0
	v_mfma_f32_16x16x32_bf16 v[116:119], v[28:31], v[124:127], v[116:119]
	v_mfma_f32_16x16x32_bf16 v[22:25], v[28:31], v[132:135], v[22:25]
	v_mfma_f32_16x16x32_bf16 v[26:29], v[32:35], v[128:131], 0
	v_mfma_f32_16x16x32_bf16 v[120:123], v[32:35], v[120:123], 0
	v_mfma_f32_16x16x32_bf16 v[26:29], v[36:39], v[132:135], v[26:29]
	v_mfma_f32_16x16x32_bf16 v[120:123], v[36:39], v[124:127], v[120:123]
	s_setprio 0
	s_barrier
; #define PG8_STAGE(bufoff, gbase, voff) do { _Pragma("unroll") for (int _i = 0; _i < 2; ++_i) \
;         __builtin_amdgcn_global_load_lds((const unsigned*)((const char*)(gbase) + (voff)[_i]), (LAS unsigned*)(lds + (bufoff) + ldsw + _i * 8192), 16, 0, 0); } while (0)
; #define PG8_LDA(dst, b, h) do { _Pragma("unroll") for (int m = 0; m < 4; ++m) _Pragma("unroll") for (int k = 0; k < 2; ++k) dst[m][k] = *(const LAS bf16x8*)(lds + PG8_SA(b, h) + aoff + m * 2048 + k * 1024); } while (0)
; #define PG8_LDB(dst, b, h) do { _Pragma("unroll") for (int n = 0; n < 2; ++n) _Pragma("unroll") for (int k = 0; k < 2; ++k) dst[n][k] = *(const LAS bf16x8*)(lds + PG8_SB(b, h) + boff + n * 2048 + k * 1024); } while (0)
; #define PG8_MMA(ai, bj, At, Bt) do { __builtin_amdgcn_s_setprio(1); _Pragma("unroll") for (int m = 0; m < 4; ++m) _Pragma("unroll") for (int n = 0; n < 2; ++n) _Pragma("unroll") for (int k = 0; k < 2; ++k) \
;         acc[ai][bj][m][n] = __builtin_amdgcn_mfma_f32_16x16x32_bf16(Bt[n][k], At[m][k], acc[ai][bj][m][n], 0, 0, 0); __builtin_amdgcn_s_setprio(0); } while (0)
; #define PG8_WAIT_V(n) asm volatile("s_waitcnt vmcnt(" #n ")" ::: "memory")
; #define PG8_WAIT_L(n) asm volatile("s_waitcnt lgkmcnt(" #n ")" ::: "memory")
; #define PG8_BAR __builtin_amdgcn_s_barrier()
; #define PG8_SCHED __builtin_amdgcn_sched_barrier(0)
; template <class Epi, bool ALIGN_EPI, int K, int LDA, int LDB>
; __device__ __forceinline__ void gemm_phase(LAS unsigned char* lds, const int wid, const Gemm g, const StaticOrder& S, const Epi& E) {
;     ...
;             PG8_LDB(B0, 1, 0); PG8_LDB(B1, 1, 1); PG8_SCHED; PG8_LDA(At, 1, 0); PG8_STAGE(PG8_SA(0, 1), a2 + hA, voffA);
;             PG8_WAIT_V(8); PG8_WAIT_L(0); PG8_BAR; PG8_MMA(0, 0, At, B0); PG8_MMA(0, 1, At, B1); PG8_BAR; PG8_SCHED;
;             PG8_LDA(At, 1, 1); PG8_STAGE(PG8_SB(1, 0), b3, voffB); PG8_STAGE(PG8_SB(1, 1), b3 + hB, voffB); PG8_STAGE(PG8_SA(1, 0), a3, voffA);
;             PG8_WAIT_V(8); PG8_WAIT_L(0); PG8_BAR; PG8_MMA(1, 0, At, B0); PG8_MMA(1, 1, At, B1); PG8_BAR; PG8_SCHED;
	s_add_i32 s69, 0, 0x18000
	s_add_i32 s70, 0, 0x1c000
	v_add_u32_e32 v8, s69, v156
	v_add_u32_e32 v9, s70, v156
	ds_read_b128 v[30:33], v8
	ds_read_b128 v[34:37], v8 offset:1024
	ds_read_b128 v[124:127], v8 offset:2048
	ds_read_b128 v[128:131], v8 offset:3072
	ds_read_b128 v[132:135], v9
	ds_read_b128 v[176:179], v9 offset:1024
	ds_read_b128 v[180:183], v9 offset:2048
	ds_read_b128 v[184:187], v9 offset:3072
	s_add_u32 s72, s36, 0xa0100
	s_addc_u32 s73, s37, 0
	s_mov_b32 m0, s54
	v_lshl_add_u64 v[38:39], s[72:73], 0, v[142:143]
	ds_read_b128 v[188:191], v157 offset:32768
	ds_read_b128 v[192:195], v157 offset:33792
	ds_read_b128 v[196:199], v157 offset:34816
	ds_read_b128 v[200:203], v157 offset:35840
	ds_read_b128 v[204:207], v157 offset:36864
	ds_read_b128 v[208:211], v157 offset:37888
	ds_read_b128 v[212:215], v157 offset:38912
	ds_read_b128 v[216:219], v157 offset:39936
	global_load_lds_dwordx4 v[38:39], off
	v_lshl_add_u64 v[38:39], s[72:73], 0, v[138:139]
	s_mov_b32 m0, s55
	s_nop 0
	global_load_lds_dwordx4 v[38:39], off
	s_waitcnt vmcnt(8)
	s_waitcnt lgkmcnt(0)
	s_barrier
	s_setprio 1
	s_waitcnt lgkmcnt(0)
	v_mfma_f32_16x16x32_bf16 v[64:67], v[30:33], v[188:191], v[64:67]
	v_mfma_f32_16x16x32_bf16 v[68:71], v[124:127], v[188:191], v[68:71]
	v_mfma_f32_16x16x32_bf16 v[72:75], v[30:33], v[196:199], v[72:75]
	v_mfma_f32_16x16x32_bf16 v[76:79], v[124:127], v[196:199], v[76:79]
	v_mfma_f32_16x16x32_bf16 v[80:83], v[30:33], v[204:207], v[80:83]
	v_mfma_f32_16x16x32_bf16 v[84:87], v[124:127], v[204:207], v[84:87]
	v_mfma_f32_16x16x32_bf16 v[88:91], v[30:33], v[212:215], v[88:91]
	v_mfma_f32_16x16x32_bf16 v[92:95], v[124:127], v[212:215], v[92:95]
	v_mfma_f32_16x16x32_bf16 v[64:67], v[34:37], v[192:195], v[64:67]
	v_mfma_f32_16x16x32_bf16 v[68:71], v[128:131], v[192:195], v[68:71]
	v_mfma_f32_16x16x32_bf16 v[72:75], v[34:37], v[200:203], v[72:75]
	v_mfma_f32_16x16x32_bf16 v[76:79], v[128:131], v[200:203], v[76:79]
	v_mfma_f32_16x16x32_bf16 v[80:83], v[34:37], v[208:211], v[80:83]
	v_mfma_f32_16x16x32_bf16 v[84:87], v[128:131], v[208:211], v[84:87]
	v_mfma_f32_16x16x32_bf16 v[88:91], v[34:37], v[216:219], v[88:91]
	v_mfma_f32_16x16x32_bf16 v[92:95], v[128:131], v[216:219], v[92:95]
	v_mfma_f32_16x16x32_bf16 v[96:99], v[132:135], v[188:191], v[96:99]
	v_mfma_f32_16x16x32_bf16 v[100:103], v[180:183], v[188:191], v[100:103]
	v_mfma_f32_16x16x32_bf16 v[104:107], v[132:135], v[196:199], v[104:107]
	v_mfma_f32_16x16x32_bf16 v[38:41], v[180:183], v[196:199], v[40:43]
	v_mfma_f32_16x16x32_bf16 v[42:45], v[132:135], v[204:207], v[44:47]
	v_mfma_f32_16x16x32_bf16 v[46:49], v[180:183], v[204:207], v[48:51]
	v_mfma_f32_16x16x32_bf16 v[50:53], v[132:135], v[212:215], v[52:55]
	v_mfma_f32_16x16x32_bf16 v[54:57], v[180:183], v[212:215], v[56:59]
	v_mfma_f32_16x16x32_bf16 v[96:99], v[176:179], v[192:195], v[96:99]
	v_mfma_f32_16x16x32_bf16 v[100:103], v[184:187], v[192:195], v[100:103]
	v_mfma_f32_16x16x32_bf16 v[104:107], v[176:179], v[200:203], v[104:107]
	v_mfma_f32_16x16x32_bf16 v[38:41], v[184:187], v[200:203], v[38:41]
	v_mfma_f32_16x16x32_bf16 v[42:45], v[176:179], v[208:211], v[42:45]
	v_mfma_f32_16x16x32_bf16 v[46:49], v[184:187], v[208:211], v[46:49]
	v_mfma_f32_16x16x32_bf16 v[50:53], v[176:179], v[216:219], v[50:53]
	v_mfma_f32_16x16x32_bf16 v[54:57], v[184:187], v[216:219], v[54:57]
	s_setprio 0
	s_barrier
	s_add_i32 s73, s69, s0
	s_add_i32 s69, s73, 0x2000
	v_lshl_add_u64 v[58:59], v[0:1], 0, s[24:25]
	s_mov_b32 m0, s73
	s_add_u32 s74, s38, 0x18180
	ds_read_b128 v[188:191], v157 offset:49152
	ds_read_b128 v[192:195], v157 offset:50176
	ds_read_b128 v[196:199], v157 offset:51200
	ds_read_b128 v[200:203], v157 offset:52224
	ds_read_b128 v[204:207], v157 offset:53248
	ds_read_b128 v[208:211], v157 offset:54272
	ds_read_b128 v[212:215], v157 offset:55296
	ds_read_b128 v[216:219], v157 offset:56320
	global_load_lds_dwordx4 v[58:59], off
	v_lshl_add_u64 v[58:59], v[2:3], 0, s[24:25]
	s_mov_b32 m0, s69
	s_addc_u32 s75, s39, 0
	s_add_i32 s70, s70, s0
	global_load_lds_dwordx4 v[58:59], off
	v_lshl_add_u64 v[58:59], s[74:75], 0, v[140:141]
	s_mov_b32 m0, s70
	s_add_i32 s72, s70, 0x2000
	global_load_lds_dwordx4 v[58:59], off
	v_lshl_add_u64 v[58:59], s[74:75], 0, v[136:137]
	s_mov_b32 m0, s72
	s_nop 0
	global_load_lds_dwordx4 v[58:59], off
	v_lshl_add_u64 v[58:59], v[4:5], 0, s[24:25]
	s_mov_b32 m0, s56
	s_nop 0
	global_load_lds_dwordx4 v[58:59], off
	v_lshl_add_u64 v[58:59], v[6:7], 0, s[24:25]
	s_mov_b32 m0, s57
	s_nop 0
	global_load_lds_dwordx4 v[58:59], off
	s_waitcnt vmcnt(8)
	s_waitcnt lgkmcnt(0)
	s_barrier
; #define PG8_STAGE(bufoff, gbase, voff) do { _Pragma("unroll") for (int _i = 0; _i < 2; ++_i) \
;         __builtin_amdgcn_global_load_lds((const unsigned*)((const char*)(gbase) + (voff)[_i]), (LAS unsigned*)(lds + (bufoff) + ldsw + _i * 8192), 16, 0, 0); } while (0)
; #define PG8_LDA(dst, b, h) do { _Pragma("unroll") for (int m = 0; m < 4; ++m) _Pragma("unroll") for (int k = 0; k < 2; ++k) dst[m][k] = *(const LAS bf16x8*)(lds + PG8_SA(b, h) + aoff + m * 2048 + k * 1024); } while (0)
; #define PG8_LDB(dst, b, h) do { _Pragma("unroll") for (int n = 0; n < 2; ++n) _Pragma("unroll") for (int k = 0; k < 2; ++k) dst[n][k] = *(const LAS bf16x8*)(lds + PG8_SB(b, h) + boff + n * 2048 + k * 1024); } while (0)
; #define PG8_MMA(ai, bj, At, Bt) do { __builtin_amdgcn_s_setprio(1); _Pragma("unroll") for (int m = 0; m < 4; ++m) _Pragma("unroll") for (int n = 0; n < 2; ++n) _Pragma("unroll") for (int k = 0; k < 2; ++k) \
;         acc[ai][bj][m][n] = __builtin_amdgcn_mfma_f32_16x16x32_bf16(Bt[n][k], At[m][k], acc[ai][bj][m][n], 0, 0, 0); __builtin_amdgcn_s_setprio(0); } while (0)
; #define PG8_WAIT_V(n) asm volatile("s_waitcnt vmcnt(" #n ")" ::: "memory")
; #define PG8_WAIT_L(n) asm volatile("s_waitcnt lgkmcnt(" #n ")" ::: "memory")
; #define PG8_BAR __builtin_amdgcn_s_barrier()
; #define PG8_SCHED __builtin_amdgcn_sched_barrier(0)
; template <class Epi, bool ALIGN_EPI, int K, int LDA, int LDB>
; __device__ __forceinline__ void gemm_phase(LAS unsigned char* lds, const int wid, const Gemm g, const StaticOrder& S, const Epi& E) {
;     ...
;             PG8_LDB(B0, 0, 0); PG8_LDB(B1, 0, 1); PG8_SCHED; PG8_LDA(At, 0, 0); PG8_STAGE(PG8_SA(1, 1), a1 + hA, voffA);
;             PG8_WAIT_V(8); PG8_WAIT_L(0); PG8_BAR; PG8_MMA(0, 0, At, B0); PG8_MMA(0, 1, At, B1); PG8_BAR; PG8_SCHED;
;     ...
;             PG8_LDA(At, 1, 1); PG8_STAGE(PG8_SB(1, 0), b3, voffB); PG8_STAGE(PG8_SB(1, 1), b3 + hB, voffB); PG8_STAGE(PG8_SA(1, 0), a3, voffA);
;             PG8_WAIT_V(8); PG8_WAIT_L(0); PG8_BAR; PG8_MMA(1, 0, At, B0); PG8_MMA(1, 1, At, B1); PG8_BAR; PG8_SCHED;
	s_setprio 1
	s_waitcnt lgkmcnt(0)
	v_mfma_f32_16x16x32_bf16 v[10:13], v[30:33], v[212:215], v[10:13]
	v_mfma_f32_16x16x32_bf16 v[14:17], v[124:127], v[212:215], v[14:17]
	v_mfma_f32_16x16x32_bf16 v[148:151], v[30:33], v[188:191], v[148:151]
	v_mfma_f32_16x16x32_bf16 v[152:155], v[124:127], v[188:191], v[152:155]
	v_mfma_f32_16x16x32_bf16 v[160:163], v[30:33], v[196:199], v[160:163]
	v_mfma_f32_16x16x32_bf16 v[164:167], v[124:127], v[196:199], v[164:167]
	v_mfma_f32_16x16x32_bf16 v[168:171], v[30:33], v[204:207], v[168:171]
	v_mfma_f32_16x16x32_bf16 v[172:175], v[124:127], v[204:207], v[172:175]
	v_mfma_f32_16x16x32_bf16 v[10:13], v[34:37], v[216:219], v[10:13]
	v_mfma_f32_16x16x32_bf16 v[14:17], v[128:131], v[216:219], v[14:17]
	v_mfma_f32_16x16x32_bf16 v[148:151], v[34:37], v[192:195], v[148:151]
	v_mfma_f32_16x16x32_bf16 v[152:155], v[128:131], v[192:195], v[152:155]
	v_mfma_f32_16x16x32_bf16 v[160:163], v[34:37], v[200:203], v[160:163]
	v_mfma_f32_16x16x32_bf16 v[164:167], v[128:131], v[200:203], v[164:167]
	v_mfma_f32_16x16x32_bf16 v[168:171], v[34:37], v[208:211], v[168:171]
	v_mfma_f32_16x16x32_bf16 v[172:175], v[128:131], v[208:211], v[172:175]
	v_mfma_f32_16x16x32_bf16 v[18:21], v[132:135], v[188:191], v[18:21]
	v_mfma_f32_16x16x32_bf16 v[30:33], v[180:183], v[188:191], v[60:63]
	v_mfma_f32_16x16x32_bf16 v[34:37], v[132:135], v[196:199], v[108:111]
	v_mfma_f32_16x16x32_bf16 v[58:61], v[180:183], v[196:199], v[112:115]
	v_mfma_f32_16x16x32_bf16 v[108:111], v[132:135], v[204:207], v[116:119]
	v_mfma_f32_16x16x32_bf16 v[112:115], v[180:183], v[204:207], v[120:123]
	v_mfma_f32_16x16x32_bf16 v[22:25], v[132:135], v[212:215], v[22:25]
	v_mfma_f32_16x16x32_bf16 v[26:29], v[180:183], v[212:215], v[26:29]
	v_mfma_f32_16x16x32_bf16 v[18:21], v[176:179], v[192:195], v[18:21]
	v_mfma_f32_16x16x32_bf16 v[30:33], v[184:187], v[192:195], v[30:33]
	v_mfma_f32_16x16x32_bf16 v[34:37], v[176:179], v[200:203], v[34:37]
	v_mfma_f32_16x16x32_bf16 v[58:61], v[184:187], v[200:203], v[58:61]
	v_mfma_f32_16x16x32_bf16 v[108:111], v[176:179], v[208:211], v[108:111]
	v_mfma_f32_16x16x32_bf16 v[112:115], v[184:187], v[208:211], v[112:115]
	v_mfma_f32_16x16x32_bf16 v[22:25], v[176:179], v[216:219], v[22:25]
	v_mfma_f32_16x16x32_bf16 v[26:29], v[184:187], v[216:219], v[26:29]
	s_setprio 0
	s_barrier
	ds_read_b128 v[116:119], v158
	ds_read_b128 v[120:123], v158 offset:1024
	ds_read_b128 v[124:127], v158 offset:2048
	ds_read_b128 v[128:131], v158 offset:3072
	ds_read_b128 v[132:135], v159
	ds_read_b128 v[176:179], v159 offset:1024
	ds_read_b128 v[180:183], v159 offset:2048
	ds_read_b128 v[184:187], v159 offset:3072
	s_add_u32 s74, s36, 0xa0180
	s_addc_u32 s75, s37, 0
	s_mov_b32 m0, s71
	v_lshl_add_u64 v[62:63], s[74:75], 0, v[142:143]
	ds_read_b128 v[188:191], v157
	ds_read_b128 v[192:195], v157 offset:1024
	ds_read_b128 v[196:199], v157 offset:2048
	ds_read_b128 v[200:203], v157 offset:3072
	ds_read_b128 v[204:207], v157 offset:4096
	ds_read_b128 v[208:211], v157 offset:5120
	ds_read_b128 v[212:215], v157 offset:6144
	ds_read_b128 v[216:219], v157 offset:7168
	global_load_lds_dwordx4 v[62:63], off
	v_lshl_add_u64 v[62:63], s[74:75], 0, v[138:139]
	s_mov_b32 m0, s6
	s_nop 0
	global_load_lds_dwordx4 v[62:63], off
	s_waitcnt vmcnt(8)
	s_waitcnt lgkmcnt(0)
	s_barrier
	s_setprio 1
	s_waitcnt lgkmcnt(0)
	v_mfma_f32_16x16x32_bf16 v[62:65], v[116:119], v[188:191], v[64:67]
	v_mfma_f32_16x16x32_bf16 v[66:69], v[124:127], v[188:191], v[68:71]
	v_mfma_f32_16x16x32_bf16 v[70:73], v[116:119], v[196:199], v[72:75]
	v_mfma_f32_16x16x32_bf16 v[74:77], v[124:127], v[196:199], v[76:79]
	v_mfma_f32_16x16x32_bf16 v[78:81], v[116:119], v[204:207], v[80:83]
	v_mfma_f32_16x16x32_bf16 v[82:85], v[124:127], v[204:207], v[84:87]
	v_mfma_f32_16x16x32_bf16 v[86:89], v[116:119], v[212:215], v[88:91]
	v_mfma_f32_16x16x32_bf16 v[90:93], v[124:127], v[212:215], v[92:95]
	v_mfma_f32_16x16x32_bf16 v[62:65], v[120:123], v[192:195], v[62:65]
	v_mfma_f32_16x16x32_bf16 v[66:69], v[128:131], v[192:195], v[66:69]
	v_mfma_f32_16x16x32_bf16 v[70:73], v[120:123], v[200:203], v[70:73]
	v_mfma_f32_16x16x32_bf16 v[74:77], v[128:131], v[200:203], v[74:77]
	v_mfma_f32_16x16x32_bf16 v[78:81], v[120:123], v[208:211], v[78:81]
	v_mfma_f32_16x16x32_bf16 v[82:85], v[128:131], v[208:211], v[82:85]
	v_mfma_f32_16x16x32_bf16 v[86:89], v[120:123], v[216:219], v[86:89]
	v_mfma_f32_16x16x32_bf16 v[90:93], v[128:131], v[216:219], v[90:93]
	v_mfma_f32_16x16x32_bf16 v[94:97], v[132:135], v[188:191], v[96:99]
	v_mfma_f32_16x16x32_bf16 v[98:101], v[180:183], v[188:191], v[100:103]
	v_mfma_f32_16x16x32_bf16 v[102:105], v[132:135], v[196:199], v[104:107]
	v_mfma_f32_16x16x32_bf16 v[38:41], v[180:183], v[196:199], v[38:41]
	v_mfma_f32_16x16x32_bf16 v[42:45], v[132:135], v[204:207], v[42:45]
	v_mfma_f32_16x16x32_bf16 v[46:49], v[180:183], v[204:207], v[46:49]
	v_mfma_f32_16x16x32_bf16 v[50:53], v[132:135], v[212:215], v[50:53]
	v_mfma_f32_16x16x32_bf16 v[54:57], v[180:183], v[212:215], v[54:57]
	v_mfma_f32_16x16x32_bf16 v[94:97], v[176:179], v[192:195], v[94:97]
	v_mfma_f32_16x16x32_bf16 v[98:101], v[184:187], v[192:195], v[98:101]
	v_mfma_f32_16x16x32_bf16 v[102:105], v[176:179], v[200:203], v[102:105]
	v_mfma_f32_16x16x32_bf16 v[38:41], v[184:187], v[200:203], v[38:41]
	v_mfma_f32_16x16x32_bf16 v[42:45], v[176:179], v[208:211], v[42:45]
	v_mfma_f32_16x16x32_bf16 v[46:49], v[184:187], v[208:211], v[46:49]
	v_mfma_f32_16x16x32_bf16 v[50:53], v[176:179], v[216:219], v[50:53]
	v_mfma_f32_16x16x32_bf16 v[54:57], v[184:187], v[216:219], v[54:57]
	s_setprio 0
	s_barrier
; #define PG8_STAGE(bufoff, gbase, voff) do { _Pragma("unroll") for (int _i = 0; _i < 2; ++_i) \
;         __builtin_amdgcn_global_load_lds((const unsigned*)((const char*)(gbase) + (voff)[_i]), (LAS unsigned*)(lds + (bufoff) + ldsw + _i * 8192), 16, 0, 0); } while (0)
; #define PG8_LDA(dst, b, h) do { _Pragma("unroll") for (int m = 0; m < 4; ++m) _Pragma("unroll") for (int k = 0; k < 2; ++k) dst[m][k] = *(const LAS bf16x8*)(lds + PG8_SA(b, h) + aoff + m * 2048 + k * 1024); } while (0)
; #define PG8_LDB(dst, b, h) do { _Pragma("unroll") for (int n = 0; n < 2; ++n) _Pragma("unroll") for (int k = 0; k < 2; ++k) dst[n][k] = *(const LAS bf16x8*)(lds + PG8_SB(b, h) + boff + n * 2048 + k * 1024); } while (0)
; #define PG8_MMA(ai, bj, At, Bt) do { __builtin_amdgcn_s_setprio(1); _Pragma("unroll") for (int m = 0; m < 4; ++m) _Pragma("unroll") for (int n = 0; n < 2; ++n) _Pragma("unroll") for (int k = 0; k < 2; ++k) \
;         acc[ai][bj][m][n] = __builtin_amdgcn_mfma_f32_16x16x32_bf16(Bt[n][k], At[m][k], acc[ai][bj][m][n], 0, 0, 0); __builtin_amdgcn_s_setprio(0); } while (0)
; #define PG8_WAIT_V(n) asm volatile("s_waitcnt vmcnt(" #n ")" ::: "memory")
; #define PG8_WAIT_L(n) asm volatile("s_waitcnt lgkmcnt(" #n ")" ::: "memory")
; #define PG8_BAR __builtin_amdgcn_s_barrier()
; #define PG8_SCHED __builtin_amdgcn_sched_barrier(0)
; template <class Epi, bool ALIGN_EPI, int K, int LDA, int LDB>
; __device__ __forceinline__ void gemm_phase(LAS unsigned char* lds, const int wid, const Gemm g, const StaticOrder& S, const Epi& E) {
;     ...
;             PG8_LDA(At, 0, 1); PG8_STAGE(PG8_SB(0, 0), b2, voffB); PG8_STAGE(PG8_SB(0, 1), b2 + hB, voffB); PG8_STAGE(PG8_SA(0, 0), a2, voffA);
;             PG8_WAIT_V(8); PG8_WAIT_L(0); PG8_BAR; PG8_MMA(1, 0, At, B0); PG8_MMA(1, 1, At, B1); PG8_BAR; PG8_SCHED;
;             PG8_LDB(B0, 1, 0); PG8_LDB(B1, 1, 1); PG8_SCHED; PG8_LDA(At, 1, 0); PG8_STAGE(PG8_SA(0, 1), a2 + hA, voffA);
;             PG8_WAIT_V(8); PG8_WAIT_L(0); PG8_BAR; PG8_MMA(0, 0, At, B0); PG8_MMA(0, 1, At, B1); PG8_BAR; PG8_SCHED;
;             PG8_LDA(At, 1, 1); PG8_STAGE(PG8_SB(1, 0), b3, voffB); PG8_STAGE(PG8_SB(1, 1), b3 + hB, voffB); PG8_STAGE(PG8_SA(1, 0), a3, voffA);
	s_mov_b32 m0, s68
	v_lshl_add_u64 v[106:107], v[0:1], 0, s[26:27]
	s_add_u32 s74, s38, 0x18200
	ds_read_b128 v[188:191], v157 offset:16384
	ds_read_b128 v[192:195], v157 offset:17408
	ds_read_b128 v[196:199], v157 offset:18432
	ds_read_b128 v[200:203], v157 offset:19456
	ds_read_b128 v[204:207], v157 offset:20480
	ds_read_b128 v[208:211], v157 offset:21504
	ds_read_b128 v[212:215], v157 offset:22528
	ds_read_b128 v[216:219], v157 offset:23552
	global_load_lds_dwordx4 v[106:107], off
	v_lshl_add_u64 v[106:107], v[2:3], 0, s[26:27]
	s_mov_b32 m0, s7
	s_addc_u32 s75, s39, 0
	global_load_lds_dwordx4 v[106:107], off
	v_lshl_add_u64 v[106:107], s[74:75], 0, v[140:141]
	s_mov_b32 m0, s66
	s_nop 0
	global_load_lds_dwordx4 v[106:107], off
	v_lshl_add_u64 v[106:107], s[74:75], 0, v[136:137]
	s_mov_b32 m0, s67
	s_nop 0
	global_load_lds_dwordx4 v[106:107], off
	v_lshl_add_u64 v[106:107], v[4:5], 0, s[26:27]
	s_mov_b32 m0, s42
	s_nop 0
	global_load_lds_dwordx4 v[106:107], off
	v_lshl_add_u64 v[106:107], v[6:7], 0, s[26:27]
	s_mov_b32 m0, s51
	s_nop 0
	global_load_lds_dwordx4 v[106:107], off
	s_waitcnt vmcnt(8)
	s_waitcnt lgkmcnt(0)
	s_barrier
	s_setprio 1
	s_waitcnt lgkmcnt(0)
	v_mfma_f32_16x16x32_bf16 v[10:13], v[116:119], v[212:215], v[10:13]
	v_mfma_f32_16x16x32_bf16 v[14:17], v[124:127], v[212:215], v[14:17]
	v_mfma_f32_16x16x32_bf16 v[148:151], v[116:119], v[188:191], v[148:151]
	v_mfma_f32_16x16x32_bf16 v[152:155], v[124:127], v[188:191], v[152:155]
	v_mfma_f32_16x16x32_bf16 v[160:163], v[116:119], v[196:199], v[160:163]
	v_mfma_f32_16x16x32_bf16 v[164:167], v[124:127], v[196:199], v[164:167]
	v_mfma_f32_16x16x32_bf16 v[168:171], v[116:119], v[204:207], v[168:171]
	v_mfma_f32_16x16x32_bf16 v[172:175], v[124:127], v[204:207], v[172:175]
	v_mfma_f32_16x16x32_bf16 v[10:13], v[120:123], v[216:219], v[10:13]
	v_mfma_f32_16x16x32_bf16 v[14:17], v[128:131], v[216:219], v[14:17]
	v_mfma_f32_16x16x32_bf16 v[148:151], v[120:123], v[192:195], v[148:151]
	v_mfma_f32_16x16x32_bf16 v[152:155], v[128:131], v[192:195], v[152:155]
	v_mfma_f32_16x16x32_bf16 v[160:163], v[120:123], v[200:203], v[160:163]
	v_mfma_f32_16x16x32_bf16 v[164:167], v[128:131], v[200:203], v[164:167]
	v_mfma_f32_16x16x32_bf16 v[168:171], v[120:123], v[208:211], v[168:171]
	v_mfma_f32_16x16x32_bf16 v[172:175], v[128:131], v[208:211], v[172:175]
	v_mfma_f32_16x16x32_bf16 v[18:21], v[132:135], v[188:191], v[18:21]
	v_mfma_f32_16x16x32_bf16 v[30:33], v[180:183], v[188:191], v[30:33]
	v_mfma_f32_16x16x32_bf16 v[34:37], v[132:135], v[196:199], v[34:37]
	v_mfma_f32_16x16x32_bf16 v[58:61], v[180:183], v[196:199], v[58:61]
	v_mfma_f32_16x16x32_bf16 v[106:109], v[132:135], v[204:207], v[108:111]
	v_mfma_f32_16x16x32_bf16 v[110:113], v[180:183], v[204:207], v[112:115]
	v_mfma_f32_16x16x32_bf16 v[22:25], v[132:135], v[212:215], v[22:25]
	v_mfma_f32_16x16x32_bf16 v[26:29], v[180:183], v[212:215], v[26:29]
	v_mfma_f32_16x16x32_bf16 v[18:21], v[176:179], v[192:195], v[18:21]
	v_mfma_f32_16x16x32_bf16 v[30:33], v[184:187], v[192:195], v[30:33]
	v_mfma_f32_16x16x32_bf16 v[34:37], v[176:179], v[200:203], v[34:37]
	v_mfma_f32_16x16x32_bf16 v[58:61], v[184:187], v[200:203], v[58:61]
	v_mfma_f32_16x16x32_bf16 v[106:109], v[176:179], v[208:211], v[106:109]
	v_mfma_f32_16x16x32_bf16 v[110:113], v[184:187], v[208:211], v[110:113]
	v_mfma_f32_16x16x32_bf16 v[22:25], v[176:179], v[216:219], v[22:25]
	v_mfma_f32_16x16x32_bf16 v[26:29], v[184:187], v[216:219], v[26:29]
	s_setprio 0
	s_barrier
	ds_read_b128 v[114:117], v8
	ds_read_b128 v[118:121], v8 offset:1024
	ds_read_b128 v[122:125], v8 offset:2048
	ds_read_b128 v[126:129], v8 offset:3072
	ds_read_b128 v[130:133], v9
	ds_read_b128 v[176:179], v9 offset:1024
	ds_read_b128 v[180:183], v9 offset:2048
	ds_read_b128 v[184:187], v9 offset:3072
	s_add_u32 s74, s36, 0xa0200
	s_addc_u32 s75, s37, 0
	s_mov_b32 m0, s54
	v_lshl_add_u64 v[134:135], s[74:75], 0, v[142:143]
	ds_read_b128 v[188:191], v157 offset:32768
	ds_read_b128 v[192:195], v157 offset:33792
	ds_read_b128 v[196:199], v157 offset:34816
	ds_read_b128 v[200:203], v157 offset:35840
	ds_read_b128 v[204:207], v157 offset:36864
	ds_read_b128 v[208:211], v157 offset:37888
	ds_read_b128 v[212:215], v157 offset:38912
	ds_read_b128 v[216:219], v157 offset:39936
	global_load_lds_dwordx4 v[134:135], off
	v_lshl_add_u64 v[134:135], s[74:75], 0, v[138:139]
	s_mov_b32 m0, s55
	s_nop 0
	global_load_lds_dwordx4 v[134:135], off
	s_waitcnt vmcnt(8)
	s_waitcnt lgkmcnt(0)
	s_barrier
	s_setprio 1
	s_waitcnt lgkmcnt(0)
	v_mfma_f32_16x16x32_bf16 v[62:65], v[114:117], v[188:191], v[62:65]
	v_mfma_f32_16x16x32_bf16 v[66:69], v[122:125], v[188:191], v[66:69]
	v_mfma_f32_16x16x32_bf16 v[70:73], v[114:117], v[196:199], v[70:73]
	v_mfma_f32_16x16x32_bf16 v[74:77], v[122:125], v[196:199], v[74:77]
	v_mfma_f32_16x16x32_bf16 v[78:81], v[114:117], v[204:207], v[78:81]
	v_mfma_f32_16x16x32_bf16 v[82:85], v[122:125], v[204:207], v[82:85]
	v_mfma_f32_16x16x32_bf16 v[86:89], v[114:117], v[212:215], v[86:89]
	v_mfma_f32_16x16x32_bf16 v[90:93], v[122:125], v[212:215], v[90:93]
	v_mfma_f32_16x16x32_bf16 v[62:65], v[118:121], v[192:195], v[62:65]
	v_mfma_f32_16x16x32_bf16 v[66:69], v[126:129], v[192:195], v[66:69]
	v_mfma_f32_16x16x32_bf16 v[70:73], v[118:121], v[200:203], v[70:73]
	v_mfma_f32_16x16x32_bf16 v[74:77], v[126:129], v[200:203], v[74:77]
	v_mfma_f32_16x16x32_bf16 v[78:81], v[118:121], v[208:211], v[78:81]
	v_mfma_f32_16x16x32_bf16 v[82:85], v[126:129], v[208:211], v[82:85]
	v_mfma_f32_16x16x32_bf16 v[86:89], v[118:121], v[216:219], v[86:89]
	v_mfma_f32_16x16x32_bf16 v[90:93], v[126:129], v[216:219], v[90:93]
	v_mfma_f32_16x16x32_bf16 v[94:97], v[130:133], v[188:191], v[94:97]
	v_mfma_f32_16x16x32_bf16 v[98:101], v[180:183], v[188:191], v[98:101]
	v_mfma_f32_16x16x32_bf16 v[102:105], v[130:133], v[196:199], v[102:105]
	v_mfma_f32_16x16x32_bf16 v[38:41], v[180:183], v[196:199], v[38:41]
	v_mfma_f32_16x16x32_bf16 v[42:45], v[130:133], v[204:207], v[42:45]
	v_mfma_f32_16x16x32_bf16 v[46:49], v[180:183], v[204:207], v[46:49]
	v_mfma_f32_16x16x32_bf16 v[50:53], v[130:133], v[212:215], v[50:53]
	v_mfma_f32_16x16x32_bf16 v[54:57], v[180:183], v[212:215], v[54:57]
	v_mfma_f32_16x16x32_bf16 v[94:97], v[176:179], v[192:195], v[94:97]
	v_mfma_f32_16x16x32_bf16 v[98:101], v[184:187], v[192:195], v[98:101]
	v_mfma_f32_16x16x32_bf16 v[102:105], v[176:179], v[200:203], v[102:105]
	v_mfma_f32_16x16x32_bf16 v[38:41], v[184:187], v[200:203], v[38:41]
	v_mfma_f32_16x16x32_bf16 v[42:45], v[176:179], v[208:211], v[42:45]
	v_mfma_f32_16x16x32_bf16 v[46:49], v[184:187], v[208:211], v[46:49]
	v_mfma_f32_16x16x32_bf16 v[50:53], v[176:179], v[216:219], v[50:53]
	v_mfma_f32_16x16x32_bf16 v[54:57], v[184:187], v[216:219], v[54:57]
	s_setprio 0
	s_barrier
; #define PG8_STAGE(bufoff, gbase, voff) do { _Pragma("unroll") for (int _i = 0; _i < 2; ++_i) \
;         __builtin_amdgcn_global_load_lds((const unsigned*)((const char*)(gbase) + (voff)[_i]), (LAS unsigned*)(lds + (bufoff) + ldsw + _i * 8192), 16, 0, 0); } while (0)
; #define PG8_LDA(dst, b, h) do { _Pragma("unroll") for (int m = 0; m < 4; ++m) _Pragma("unroll") for (int k = 0; k < 2; ++k) dst[m][k] = *(const LAS bf16x8*)(lds + PG8_SA(b, h) + aoff + m * 2048 + k * 1024); } while (0)
; #define PG8_LDB(dst, b, h) do { _Pragma("unroll") for (int n = 0; n < 2; ++n) _Pragma("unroll") for (int k = 0; k < 2; ++k) dst[n][k] = *(const LAS bf16x8*)(lds + PG8_SB(b, h) + boff + n * 2048 + k * 1024); } while (0)
; #define PG8_MMA(ai, bj, At, Bt) do { __builtin_amdgcn_s_setprio(1); _Pragma("unroll") for (int m = 0; m < 4; ++m) _Pragma("unroll") for (int n = 0; n < 2; ++n) _Pragma("unroll") for (int k = 0; k < 2; ++k) \
;         acc[ai][bj][m][n] = __builtin_amdgcn_mfma_f32_16x16x32_bf16(Bt[n][k], At[m][k], acc[ai][bj][m][n], 0, 0, 0); __builtin_amdgcn_s_setprio(0); } while (0)
; #define PG8_WAIT_V(n) asm volatile("s_waitcnt vmcnt(" #n ")" ::: "memory")
; #define PG8_WAIT_L(n) asm volatile("s_waitcnt lgkmcnt(" #n ")" ::: "memory")
; #define PG8_BAR __builtin_amdgcn_s_barrier()
; #define PG8_SCHED __builtin_amdgcn_sched_barrier(0)
; template <class Epi, bool ALIGN_EPI, int K, int LDA, int LDB>
; __device__ __forceinline__ void gemm_phase(LAS unsigned char* lds, const int wid, const Gemm g, const StaticOrder& S, const Epi& E) {
;     ...
;             PG8_LDB(B0, 0, 0); PG8_LDB(B1, 0, 1); PG8_SCHED; PG8_LDA(At, 0, 0); PG8_STAGE(PG8_SA(1, 1), a1 + hA, voffA);
;             PG8_WAIT_V(8); PG8_WAIT_L(0); PG8_BAR; PG8_MMA(0, 0, At, B0); PG8_MMA(0, 1, At, B1); PG8_BAR; PG8_SCHED;
;     ...
;             PG8_LDA(At, 1, 1); PG8_STAGE(PG8_SB(1, 0), b3, voffB); PG8_STAGE(PG8_SB(1, 1), b3 + hB, voffB); PG8_STAGE(PG8_SA(1, 0), a3, voffA);
;             PG8_WAIT_V(8); PG8_WAIT_L(0); PG8_BAR; PG8_MMA(1, 0, At, B0); PG8_MMA(1, 1, At, B1); PG8_BAR; PG8_SCHED;
	s_mov_b32 m0, s73
	v_lshl_add_u64 v[0:1], v[0:1], 0, s[28:29]
	s_add_u32 s38, s38, 0x18280
	ds_read_b128 v[188:191], v157 offset:49152
	ds_read_b128 v[192:195], v157 offset:50176
	ds_read_b128 v[196:199], v157 offset:51200
	ds_read_b128 v[200:203], v157 offset:52224
	ds_read_b128 v[204:207], v157 offset:53248
	ds_read_b128 v[208:211], v157 offset:54272
	ds_read_b128 v[212:215], v157 offset:55296
	ds_read_b128 v[216:219], v157 offset:56320
	global_load_lds_dwordx4 v[0:1], off
	v_lshl_add_u64 v[0:1], v[2:3], 0, s[28:29]
	s_mov_b32 m0, s69
	s_addc_u32 s39, s39, 0
	global_load_lds_dwordx4 v[0:1], off
	v_lshl_add_u64 v[0:1], s[38:39], 0, v[140:141]
	s_mov_b32 m0, s70
	s_nop 0
	global_load_lds_dwordx4 v[0:1], off
	v_lshl_add_u64 v[0:1], s[38:39], 0, v[136:137]
	s_mov_b32 m0, s72
	s_nop 0
	global_load_lds_dwordx4 v[0:1], off
	v_lshl_add_u64 v[0:1], v[4:5], 0, s[28:29]
	s_mov_b32 m0, s56
	s_nop 0
	global_load_lds_dwordx4 v[0:1], off
	v_lshl_add_u64 v[0:1], v[6:7], 0, s[28:29]
	s_mov_b32 m0, s57
	s_nop 0
	global_load_lds_dwordx4 v[0:1], off
	s_waitcnt vmcnt(8)
	s_waitcnt lgkmcnt(0)
	s_barrier
	s_setprio 1
	s_waitcnt lgkmcnt(0)
	v_mfma_f32_16x16x32_bf16 v[0:3], v[114:117], v[188:191], v[148:151]
	v_mfma_f32_16x16x32_bf16 v[4:7], v[122:125], v[188:191], v[152:155]
	v_mfma_f32_16x16x32_bf16 v[10:13], v[114:117], v[212:215], v[10:13]
	v_mfma_f32_16x16x32_bf16 v[14:17], v[122:125], v[212:215], v[14:17]
	v_mfma_f32_16x16x32_bf16 v[0:3], v[118:121], v[192:195], v[0:3]
	v_mfma_f32_16x16x32_bf16 v[4:7], v[126:129], v[192:195], v[4:7]
	v_mfma_f32_16x16x32_bf16 v[148:151], v[114:117], v[196:199], v[160:163]
	v_mfma_f32_16x16x32_bf16 v[152:155], v[122:125], v[196:199], v[164:167]
	v_mfma_f32_16x16x32_bf16 v[160:163], v[114:117], v[204:207], v[168:171]
	v_mfma_f32_16x16x32_bf16 v[164:167], v[122:125], v[204:207], v[172:175]
	v_mfma_f32_16x16x32_bf16 v[10:13], v[118:121], v[216:219], v[10:13]
	v_mfma_f32_16x16x32_bf16 v[14:17], v[126:129], v[216:219], v[14:17]
	v_mfma_f32_16x16x32_bf16 v[148:151], v[118:121], v[200:203], v[148:151]
	v_mfma_f32_16x16x32_bf16 v[152:155], v[126:129], v[200:203], v[152:155]
	v_mfma_f32_16x16x32_bf16 v[160:163], v[118:121], v[208:211], v[160:163]
	v_mfma_f32_16x16x32_bf16 v[164:167], v[126:129], v[208:211], v[164:167]
	v_mfma_f32_16x16x32_bf16 v[18:21], v[130:133], v[188:191], v[18:21]
	v_mfma_f32_16x16x32_bf16 v[30:33], v[180:183], v[188:191], v[30:33]
	v_mfma_f32_16x16x32_bf16 v[34:37], v[130:133], v[196:199], v[34:37]
	v_mfma_f32_16x16x32_bf16 v[58:61], v[180:183], v[196:199], v[58:61]
	v_mfma_f32_16x16x32_bf16 v[106:109], v[130:133], v[204:207], v[106:109]
	v_mfma_f32_16x16x32_bf16 v[110:113], v[180:183], v[204:207], v[110:113]
	v_mfma_f32_16x16x32_bf16 v[22:25], v[130:133], v[212:215], v[22:25]
	v_mfma_f32_16x16x32_bf16 v[26:29], v[180:183], v[212:215], v[26:29]
	v_mfma_f32_16x16x32_bf16 v[18:21], v[176:179], v[192:195], v[18:21]
	v_mfma_f32_16x16x32_bf16 v[30:33], v[184:187], v[192:195], v[30:33]
	v_mfma_f32_16x16x32_bf16 v[34:37], v[176:179], v[200:203], v[34:37]
	v_mfma_f32_16x16x32_bf16 v[58:61], v[184:187], v[200:203], v[58:61]
	v_mfma_f32_16x16x32_bf16 v[106:109], v[176:179], v[208:211], v[106:109]
	v_mfma_f32_16x16x32_bf16 v[110:113], v[184:187], v[208:211], v[110:113]
	v_mfma_f32_16x16x32_bf16 v[22:25], v[176:179], v[216:219], v[22:25]
	v_mfma_f32_16x16x32_bf16 v[26:29], v[184:187], v[216:219], v[26:29]
	s_setprio 0
	s_barrier
	ds_read_b128 v[114:117], v158
	ds_read_b128 v[118:121], v158 offset:1024
	ds_read_b128 v[122:125], v158 offset:2048
	ds_read_b128 v[126:129], v158 offset:3072
	ds_read_b128 v[130:133], v159
	ds_read_b128 v[168:171], v159 offset:1024
	ds_read_b128 v[172:175], v159 offset:2048
	ds_read_b128 v[176:179], v159 offset:3072
	s_add_u32 s36, s36, 0xa0280
	s_addc_u32 s37, s37, 0
	s_mov_b32 m0, s71
	v_lshl_add_u64 v[134:135], s[36:37], 0, v[142:143]
	ds_read_b128 v[180:183], v157
	ds_read_b128 v[184:187], v157 offset:1024
	ds_read_b128 v[188:191], v157 offset:2048
	ds_read_b128 v[192:195], v157 offset:3072
	ds_read_b128 v[196:199], v157 offset:4096
	ds_read_b128 v[200:203], v157 offset:5120
	ds_read_b128 v[204:207], v157 offset:6144
	ds_read_b128 v[208:211], v157 offset:7168
	global_load_lds_dwordx4 v[134:135], off
	v_lshl_add_u64 v[134:135], s[36:37], 0, v[138:139]
	s_mov_b32 m0, s6
	s_nop 0
	global_load_lds_dwordx4 v[134:135], off
	s_waitcnt vmcnt(8)
	s_waitcnt lgkmcnt(0)
	s_barrier
	s_setprio 1
	s_waitcnt lgkmcnt(0)
	v_mfma_f32_16x16x32_bf16 v[62:65], v[114:117], v[180:183], v[62:65]
	v_mfma_f32_16x16x32_bf16 v[66:69], v[122:125], v[180:183], v[66:69]
	v_mfma_f32_16x16x32_bf16 v[70:73], v[114:117], v[188:191], v[70:73]
	v_mfma_f32_16x16x32_bf16 v[74:77], v[122:125], v[188:191], v[74:77]
	v_mfma_f32_16x16x32_bf16 v[78:81], v[114:117], v[196:199], v[78:81]
	v_mfma_f32_16x16x32_bf16 v[82:85], v[122:125], v[196:199], v[82:85]
	v_mfma_f32_16x16x32_bf16 v[86:89], v[114:117], v[204:207], v[86:89]
	v_mfma_f32_16x16x32_bf16 v[62:65], v[118:121], v[184:187], v[62:65]
	v_mfma_f32_16x16x32_bf16 v[66:69], v[126:129], v[184:187], v[66:69]
	v_mfma_f32_16x16x32_bf16 v[70:73], v[118:121], v[192:195], v[70:73]
	v_mfma_f32_16x16x32_bf16 v[74:77], v[126:129], v[192:195], v[74:77]
	v_mfma_f32_16x16x32_bf16 v[78:81], v[118:121], v[200:203], v[78:81]
	v_mfma_f32_16x16x32_bf16 v[82:85], v[126:129], v[200:203], v[82:85]
	v_mfma_f32_16x16x32_bf16 v[212:215], v[118:121], v[208:211], v[86:89]
	v_mfma_f32_16x16x32_bf16 v[86:89], v[122:125], v[204:207], v[90:93]
	v_mfma_f32_16x16x32_bf16 v[216:219], v[126:129], v[208:211], v[86:89]
	v_mfma_f32_16x16x32_bf16 v[86:89], v[130:133], v[180:183], v[94:97]
	v_mfma_f32_16x16x32_bf16 v[220:223], v[168:171], v[184:187], v[86:89]
	v_mfma_f32_16x16x32_bf16 v[86:89], v[172:175], v[180:183], v[98:101]
	v_mfma_f32_16x16x32_bf16 v[96:99], v[176:179], v[184:187], v[86:89]
	v_mfma_f32_16x16x32_bf16 v[86:89], v[130:133], v[188:191], v[102:105]
	v_mfma_f32_16x16x32_bf16 v[38:41], v[172:175], v[188:191], v[38:41]
	v_mfma_f32_16x16x32_bf16 v[42:45], v[130:133], v[196:199], v[42:45]
	v_mfma_f32_16x16x32_bf16 v[46:49], v[172:175], v[196:199], v[46:49]
	v_mfma_f32_16x16x32_bf16 v[50:53], v[130:133], v[204:207], v[50:53]
	v_mfma_f32_16x16x32_bf16 v[54:57], v[172:175], v[204:207], v[54:57]
	v_mfma_f32_16x16x32_bf16 v[100:103], v[168:171], v[192:195], v[86:89]
	v_mfma_f32_16x16x32_bf16 v[38:41], v[176:179], v[192:195], v[38:41]
	v_mfma_f32_16x16x32_bf16 v[42:45], v[168:171], v[200:203], v[42:45]
	v_mfma_f32_16x16x32_bf16 v[46:49], v[176:179], v[200:203], v[46:49]
	v_mfma_f32_16x16x32_bf16 v[50:53], v[168:171], v[208:211], v[50:53]
	v_mfma_f32_16x16x32_bf16 v[54:57], v[176:179], v[208:211], v[54:57]
	s_setprio 0
	s_barrier
; #define PG8_STAGE(bufoff, gbase, voff) do { _Pragma("unroll") for (int _i = 0; _i < 2; ++_i) \
;         __builtin_amdgcn_global_load_lds((const unsigned*)((const char*)(gbase) + (voff)[_i]), (LAS unsigned*)(lds + (bufoff) + ldsw + _i * 8192), 16, 0, 0); } while (0)
; #define PG8_LDA(dst, b, h) do { _Pragma("unroll") for (int m = 0; m < 4; ++m) _Pragma("unroll") for (int k = 0; k < 2; ++k) dst[m][k] = *(const LAS bf16x8*)(lds + PG8_SA(b, h) + aoff + m * 2048 + k * 1024); } while (0)
; #define PG8_LDB(dst, b, h) do { _Pragma("unroll") for (int n = 0; n < 2; ++n) _Pragma("unroll") for (int k = 0; k < 2; ++k) dst[n][k] = *(const LAS bf16x8*)(lds + PG8_SB(b, h) + boff + n * 2048 + k * 1024); } while (0)
; #define PG8_MMA(ai, bj, At, Bt) do { __builtin_amdgcn_s_setprio(1); _Pragma("unroll") for (int m = 0; m < 4; ++m) _Pragma("unroll") for (int n = 0; n < 2; ++n) _Pragma("unroll") for (int k = 0; k < 2; ++k) \
;         acc[ai][bj][m][n] = __builtin_amdgcn_mfma_f32_16x16x32_bf16(Bt[n][k], At[m][k], acc[ai][bj][m][n], 0, 0, 0); __builtin_amdgcn_s_setprio(0); } while (0)
; #define PG8_WAIT_V(n) asm volatile("s_waitcnt vmcnt(" #n ")" ::: "memory")
; #define PG8_WAIT_L(n) asm volatile("s_waitcnt lgkmcnt(" #n ")" ::: "memory")
; #define PG8_BAR __builtin_amdgcn_s_barrier()
; #define PG8_SCHED __builtin_amdgcn_sched_barrier(0)
; template <class Epi, bool ALIGN_EPI, int K, int LDA, int LDB>
; __device__ __forceinline__ void gemm_phase(LAS unsigned char* lds, const int wid, const Gemm g, const StaticOrder& S, const Epi& E) {
;     ...
;             PG8_LDA(At, 0, 1); PG8_STAGE(PG8_SB(0, 0), b2, voffB); PG8_STAGE(PG8_SB(0, 1), b2 + hB, voffB); PG8_STAGE(PG8_SA(0, 0), a2, voffA);
;             PG8_WAIT_V(8); PG8_WAIT_L(0); PG8_BAR; PG8_MMA(1, 0, At, B0); PG8_MMA(1, 1, At, B1); PG8_BAR; PG8_SCHED;
;             PG8_LDB(B0, 1, 0); PG8_LDB(B1, 1, 1); PG8_SCHED; PG8_LDA(At, 1, 0); PG8_STAGE(PG8_SA(0, 1), a2 + hA, voffA);
;             PG8_WAIT_V(8); PG8_WAIT_L(0); PG8_BAR; PG8_MMA(0, 0, At, B0); PG8_MMA(0, 1, At, B1); PG8_BAR; PG8_SCHED;
;             PG8_LDA(At, 1, 1); PG8_STAGE(PG8_SB(1, 0), b3, voffB); PG8_STAGE(PG8_SB(1, 1), b3 + hB, voffB); PG8_STAGE(PG8_SA(1, 0), a3, voffA);
;             PG8_WAIT_V(8); PG8_WAIT_L(0); PG8_BAR; PG8_MMA(1, 0, At, B0); PG8_MMA(1, 1, At, B1); PG8_BAR; PG8_SCHED;
	s_mov_b32 m0, s68
	v_lshl_add_u64 v[248:249], s[34:35], 0, v[140:141]
	s_add_u32 s6, s34, 0x18000
	ds_read_b128 v[86:89], v157 offset:16384
	ds_read_b128 v[90:93], v157 offset:17408
	ds_read_b128 v[180:183], v157 offset:18432
	ds_read_b128 v[184:187], v157 offset:19456
	ds_read_b128 v[188:191], v157 offset:20480
	ds_read_b128 v[192:195], v157 offset:21504
	ds_read_b128 v[196:199], v157 offset:22528
	ds_read_b128 v[200:203], v157 offset:23552
	global_load_lds_dwordx4 v[248:249], off
	v_lshl_add_u64 v[250:251], s[34:35], 0, v[136:137]
	s_mov_b32 m0, s7
	s_addc_u32 s7, s35, 0
	global_load_lds_dwordx4 v[250:251], off
	v_lshl_add_u64 v[94:95], s[6:7], 0, v[140:141]
	s_mov_b32 m0, s66
	v_lshl_add_u64 v[252:253], s[30:31], 0, v[142:143]
	global_load_lds_dwordx4 v[94:95], off
	v_lshl_add_u64 v[94:95], s[6:7], 0, v[136:137]
	s_mov_b32 m0, s67
	v_lshl_add_u64 v[144:145], s[30:31], 0, v[138:139]
	global_load_lds_dwordx4 v[94:95], off
	s_mov_b32 m0, s42
	s_nop 0
	global_load_lds_dwordx4 v[252:253], off
	s_mov_b32 m0, s51
	s_nop 0
	global_load_lds_dwordx4 v[144:145], off
	s_waitcnt vmcnt(8)
	s_waitcnt lgkmcnt(0)
	s_barrier
	s_setprio 1
	s_waitcnt lgkmcnt(0)
	v_mfma_f32_16x16x32_bf16 v[0:3], v[114:117], v[86:89], v[0:3]
	v_mfma_f32_16x16x32_bf16 v[4:7], v[122:125], v[86:89], v[4:7]
	v_mfma_f32_16x16x32_bf16 v[10:13], v[114:117], v[196:199], v[10:13]
	v_mfma_f32_16x16x32_bf16 v[0:3], v[118:121], v[90:93], v[0:3]
	v_mfma_f32_16x16x32_bf16 v[4:7], v[126:129], v[90:93], v[4:7]
	v_mfma_f32_16x16x32_bf16 v[148:151], v[114:117], v[180:183], v[148:151]
	v_mfma_f32_16x16x32_bf16 v[152:155], v[122:125], v[180:183], v[152:155]
	v_mfma_f32_16x16x32_bf16 v[160:163], v[114:117], v[188:191], v[160:163]
	v_mfma_f32_16x16x32_bf16 v[164:167], v[122:125], v[188:191], v[164:167]
	v_mfma_f32_16x16x32_bf16 v[10:13], v[118:121], v[200:203], v[10:13]
	v_mfma_f32_16x16x32_bf16 v[14:17], v[122:125], v[196:199], v[14:17]
	v_mfma_f32_16x16x32_bf16 v[148:151], v[118:121], v[184:187], v[148:151]
	v_mfma_f32_16x16x32_bf16 v[152:155], v[126:129], v[184:187], v[152:155]
	v_mfma_f32_16x16x32_bf16 v[160:163], v[118:121], v[192:195], v[160:163]
	v_mfma_f32_16x16x32_bf16 v[164:167], v[126:129], v[192:195], v[164:167]
	v_mfma_f32_16x16x32_bf16 v[120:123], v[126:129], v[200:203], v[14:17]
	v_mfma_f32_16x16x32_bf16 v[30:33], v[172:175], v[86:89], v[30:33]
	v_mfma_f32_16x16x32_bf16 v[58:61], v[172:175], v[180:183], v[58:61]
	v_mfma_f32_16x16x32_bf16 v[14:17], v[130:133], v[86:89], v[18:21]
	v_mfma_f32_16x16x32_bf16 v[124:127], v[176:179], v[90:93], v[30:33]
	v_mfma_f32_16x16x32_bf16 v[30:33], v[130:133], v[180:183], v[34:37]
	v_mfma_f32_16x16x32_bf16 v[180:183], v[176:179], v[184:187], v[58:61]
	v_mfma_f32_16x16x32_bf16 v[58:61], v[130:133], v[188:191], v[106:109]
	v_mfma_f32_16x16x32_bf16 v[20:23], v[130:133], v[196:199], v[22:25]
	v_mfma_f32_16x16x32_bf16 v[16:19], v[168:171], v[90:93], v[14:17]
	v_mfma_f32_16x16x32_bf16 v[32:35], v[168:171], v[184:187], v[30:33]
	v_mfma_f32_16x16x32_bf16 v[184:187], v[168:171], v[192:195], v[58:61]
	v_mfma_f32_16x16x32_bf16 v[58:61], v[172:175], v[188:191], v[110:113]
	v_mfma_f32_16x16x32_bf16 v[168:171], v[168:171], v[200:203], v[20:23]
	v_mfma_f32_16x16x32_bf16 v[20:23], v[172:175], v[196:199], v[26:29]
	v_mfma_f32_16x16x32_bf16 v[188:191], v[176:179], v[192:195], v[58:61]
	v_mfma_f32_16x16x32_bf16 v[172:175], v[176:179], v[200:203], v[20:23]
	s_setprio 0
	s_barrier
	s_nop 3
	ds_read_b128 v[20:23], v8
	ds_read_b128 v[176:179], v8 offset:1024
	ds_read_b128 v[192:195], v8 offset:2048
	ds_read_b128 v[196:199], v8 offset:3072
	ds_read_b128 v[200:203], v9
	ds_read_b128 v[204:207], v9 offset:1024
	ds_read_b128 v[208:211], v9 offset:2048
	ds_read_b128 v[224:227], v9 offset:3072
	s_add_u32 s6, s30, 0xa0000
	s_addc_u32 s7, s31, 0
	s_mov_b32 m0, s54
	v_lshl_add_u64 v[8:9], s[6:7], 0, v[142:143]
	ds_read_b128 v[24:27], v157 offset:32768
	ds_read_b128 v[28:31], v157 offset:33792
	ds_read_b128 v[58:61], v157 offset:34816
	ds_read_b128 v[228:231], v157 offset:35840
	ds_read_b128 v[232:235], v157 offset:36864
	ds_read_b128 v[236:239], v157 offset:37888
	ds_read_b128 v[240:243], v157 offset:38912
	ds_read_b128 v[244:247], v157 offset:39936
	global_load_lds_dwordx4 v[8:9], off
	v_lshl_add_u64 v[8:9], s[6:7], 0, v[138:139]
	s_mov_b32 m0, s55
	s_nop 0
	global_load_lds_dwordx4 v[8:9], off
	s_waitcnt vmcnt(8)
	s_waitcnt lgkmcnt(0)
	s_barrier
; __device__ __forceinline__ int lane_id_() { int l; asm volatile("v_mbcnt_lo_u32_b32 %0, -1, 0\n\tv_mbcnt_hi_u32_b32 %0, -1, %0" : "=v"(l)); return l; }
; #define PG8_STAGE(bufoff, gbase, voff) do { _Pragma("unroll") for (int _i = 0; _i < 2; ++_i) \
;         __builtin_amdgcn_global_load_lds((const unsigned*)((const char*)(gbase) + (voff)[_i]), (LAS unsigned*)(lds + (bufoff) + ldsw + _i * 8192), 16, 0, 0); } while (0)
; #define PG8_LDA(dst, b, h) do { _Pragma("unroll") for (int m = 0; m < 4; ++m) _Pragma("unroll") for (int k = 0; k < 2; ++k) dst[m][k] = *(const LAS bf16x8*)(lds + PG8_SA(b, h) + aoff + m * 2048 + k * 1024); } while (0)
; #define PG8_MMA(ai, bj, At, Bt) do { __builtin_amdgcn_s_setprio(1); _Pragma("unroll") for (int m = 0; m < 4; ++m) _Pragma("unroll") for (int n = 0; n < 2; ++n) _Pragma("unroll") for (int k = 0; k < 2; ++k) \
;         acc[ai][bj][m][n] = __builtin_amdgcn_mfma_f32_16x16x32_bf16(Bt[n][k], At[m][k], acc[ai][bj][m][n], 0, 0, 0); __builtin_amdgcn_s_setprio(0); } while (0)
; #define PG8_WAIT_V(n) asm volatile("s_waitcnt vmcnt(" #n ")" ::: "memory")
; #define PG8_WAIT_L(n) asm volatile("s_waitcnt lgkmcnt(" #n ")" ::: "memory")
; #define PG8_BAR __builtin_amdgcn_s_barrier()
; #define PG8_SCHED __builtin_amdgcn_sched_barrier(0)
; template <class Epi, bool ALIGN_EPI, int K, int LDA, int LDB>
; __device__ __forceinline__ void gemm_phase(LAS unsigned char* lds, const int wid, const Gemm g, const StaticOrder& S, const Epi& E) {
;     ...
;             PG8_LDA(At, 1, 1); PG8_STAGE(PG8_SB(1, 0), b3, voffB); PG8_STAGE(PG8_SB(1, 1), b3 + hB, voffB); PG8_STAGE(PG8_SA(1, 0), a3, voffA);
;             PG8_WAIT_V(8); PG8_WAIT_L(0); PG8_BAR; PG8_MMA(1, 0, At, B0); PG8_MMA(1, 1, At, B1); PG8_BAR; PG8_SCHED;
;         }
;         if constexpr (ALIGN_EPI) { if (wr == 0) PG8_BAR; }
;         { const int l2 = lane_id_(); E(acc, cur, wid >> 2, wid & 3, l2 & 15, l2 >> 4); }
;         if (!has_next) break;
	s_setprio 1
	s_waitcnt lgkmcnt(0)
	v_mfma_f32_16x16x32_bf16 v[62:65], v[20:23], v[24:27], v[62:65]
	v_mfma_f32_16x16x32_bf16 v[128:131], v[176:179], v[28:31], v[62:65]
	v_mfma_f32_16x16x32_bf16 v[62:65], v[192:195], v[24:27], v[66:69]
	v_mfma_f32_16x16x32_bf16 v[132:135], v[196:199], v[28:31], v[62:65]
	v_mfma_f32_16x16x32_bf16 v[62:65], v[20:23], v[58:61], v[70:73]
	v_mfma_f32_16x16x32_bf16 v[108:111], v[176:179], v[228:231], v[62:65]
	v_mfma_f32_16x16x32_bf16 v[62:65], v[192:195], v[58:61], v[74:77]
	v_mfma_f32_16x16x32_bf16 v[104:107], v[196:199], v[228:231], v[62:65]
	v_mfma_f32_16x16x32_bf16 v[62:65], v[20:23], v[232:235], v[78:81]
	v_mfma_f32_16x16x32_bf16 v[92:95], v[176:179], v[236:239], v[62:65]
	v_mfma_f32_16x16x32_bf16 v[62:65], v[192:195], v[232:235], v[82:85]
	v_mfma_f32_16x16x32_bf16 v[88:91], v[196:199], v[236:239], v[62:65]
	v_mfma_f32_16x16x32_bf16 v[62:65], v[20:23], v[240:243], v[212:215]
	v_mfma_f32_16x16x32_bf16 v[76:79], v[176:179], v[244:247], v[62:65]
	v_mfma_f32_16x16x32_bf16 v[62:65], v[192:195], v[240:243], v[216:219]
	v_mfma_f32_16x16x32_bf16 v[72:75], v[196:199], v[244:247], v[62:65]
	v_mfma_f32_16x16x32_bf16 v[62:65], v[200:203], v[24:27], v[220:223]
	v_mfma_f32_16x16x32_bf16 v[24:27], v[208:211], v[24:27], v[96:99]
	v_mfma_f32_16x16x32_bf16 v[112:115], v[224:227], v[28:31], v[24:27]
	v_mfma_f32_16x16x32_bf16 v[24:27], v[200:203], v[58:61], v[100:103]
	v_mfma_f32_16x16x32_bf16 v[100:103], v[204:207], v[228:231], v[24:27]
	v_mfma_f32_16x16x32_bf16 v[24:27], v[208:211], v[58:61], v[38:41]
	v_mfma_f32_16x16x32_bf16 v[96:99], v[224:227], v[228:231], v[24:27]
	v_mfma_f32_16x16x32_bf16 v[24:27], v[200:203], v[232:235], v[42:45]
	v_mfma_f32_16x16x32_bf16 v[84:87], v[204:207], v[236:239], v[24:27]
	v_mfma_f32_16x16x32_bf16 v[24:27], v[208:211], v[232:235], v[46:49]
	v_mfma_f32_16x16x32_bf16 v[80:83], v[224:227], v[236:239], v[24:27]
	v_mfma_f32_16x16x32_bf16 v[24:27], v[200:203], v[240:243], v[50:53]
	v_mfma_f32_16x16x32_bf16 v[68:71], v[204:207], v[244:247], v[24:27]
	v_mfma_f32_16x16x32_bf16 v[24:27], v[208:211], v[240:243], v[54:57]
	v_mfma_f32_16x16x32_bf16 v[116:119], v[204:207], v[28:31], v[62:65]
	v_mfma_f32_16x16x32_bf16 v[64:67], v[224:227], v[244:247], v[24:27]
	s_setprio 0
	s_barrier
	s_mov_b32 m0, s73
	v_lshl_add_u64 v[8:9], v[248:249], 0, s[16:17]
	s_add_u32 s6, s34, 0x18080
	ds_read_b128 v[36:39], v157 offset:49152
	ds_read_b128 v[48:51], v157 offset:50176
	ds_read_b128 v[212:215], v157 offset:51200
	ds_read_b128 v[216:219], v157 offset:52224
	ds_read_b128 v[220:223], v157 offset:53248
	ds_read_b128 v[228:231], v157 offset:54272
	ds_read_b128 v[232:235], v157 offset:55296
	ds_read_b128 v[236:239], v157 offset:56320
	global_load_lds_dwordx4 v[8:9], off
	v_lshl_add_u64 v[8:9], v[250:251], 0, s[16:17]
	s_mov_b32 m0, s69
	s_addc_u32 s7, s35, 0
	global_load_lds_dwordx4 v[8:9], off
	v_lshl_add_u64 v[8:9], s[6:7], 0, v[140:141]
	s_mov_b32 m0, s70
	s_nop 0
	global_load_lds_dwordx4 v[8:9], off
	v_lshl_add_u64 v[8:9], s[6:7], 0, v[136:137]
	s_mov_b32 m0, s72
	s_nop 0
	global_load_lds_dwordx4 v[8:9], off
	v_lshl_add_u64 v[8:9], v[252:253], 0, s[16:17]
	s_mov_b32 m0, s56
	s_nop 0
	global_load_lds_dwordx4 v[8:9], off
	v_lshl_add_u64 v[8:9], v[144:145], 0, s[16:17]
	s_mov_b32 m0, s57
	s_nop 0
	global_load_lds_dwordx4 v[8:9], off
	s_waitcnt vmcnt(8)
	s_waitcnt lgkmcnt(0)
	s_barrier
	s_setprio 1
	s_waitcnt lgkmcnt(0)
	v_mfma_f32_16x16x32_bf16 v[0:3], v[20:23], v[36:39], v[0:3]
	v_mfma_f32_16x16x32_bf16 v[60:63], v[176:179], v[48:51], v[0:3]
	v_mfma_f32_16x16x32_bf16 v[0:3], v[192:195], v[36:39], v[4:7]
	v_mfma_f32_16x16x32_bf16 v[56:59], v[196:199], v[48:51], v[0:3]
	v_mfma_f32_16x16x32_bf16 v[0:3], v[20:23], v[212:215], v[148:151]
	v_mfma_f32_16x16x32_bf16 v[44:47], v[176:179], v[216:219], v[0:3]
	v_mfma_f32_16x16x32_bf16 v[0:3], v[192:195], v[212:215], v[152:155]
	v_mfma_f32_16x16x32_bf16 v[40:43], v[196:199], v[216:219], v[0:3]
	v_mfma_f32_16x16x32_bf16 v[0:3], v[20:23], v[220:223], v[160:163]
	v_mfma_f32_16x16x32_bf16 v[28:31], v[176:179], v[228:231], v[0:3]
	v_mfma_f32_16x16x32_bf16 v[0:3], v[192:195], v[220:223], v[164:167]
	v_mfma_f32_16x16x32_bf16 v[24:27], v[196:199], v[228:231], v[0:3]
	v_mfma_f32_16x16x32_bf16 v[0:3], v[20:23], v[232:235], v[10:13]
	v_mfma_f32_16x16x32_bf16 v[12:15], v[176:179], v[236:239], v[0:3]
	v_mfma_f32_16x16x32_bf16 v[0:3], v[192:195], v[232:235], v[120:123]
	v_mfma_f32_16x16x32_bf16 v[8:11], v[196:199], v[236:239], v[0:3]
	v_mfma_f32_16x16x32_bf16 v[0:3], v[200:203], v[36:39], v[16:19]
	v_mfma_f32_16x16x32_bf16 v[52:55], v[204:207], v[48:51], v[0:3]
	v_mfma_f32_16x16x32_bf16 v[0:3], v[208:211], v[36:39], v[124:127]
	v_mfma_f32_16x16x32_bf16 v[48:51], v[224:227], v[48:51], v[0:3]
	v_mfma_f32_16x16x32_bf16 v[0:3], v[200:203], v[212:215], v[32:35]
	v_mfma_f32_16x16x32_bf16 v[36:39], v[204:207], v[216:219], v[0:3]
	v_mfma_f32_16x16x32_bf16 v[0:3], v[208:211], v[212:215], v[180:183]
	v_mfma_f32_16x16x32_bf16 v[32:35], v[224:227], v[216:219], v[0:3]
	v_mfma_f32_16x16x32_bf16 v[0:3], v[200:203], v[220:223], v[184:187]
	v_mfma_f32_16x16x32_bf16 v[20:23], v[204:207], v[228:231], v[0:3]
	v_mfma_f32_16x16x32_bf16 v[0:3], v[208:211], v[220:223], v[188:191]
	v_mfma_f32_16x16x32_bf16 v[16:19], v[224:227], v[228:231], v[0:3]
	v_mfma_f32_16x16x32_bf16 v[0:3], v[200:203], v[232:235], v[168:171]
	v_mfma_f32_16x16x32_bf16 v[4:7], v[204:207], v[236:239], v[0:3]
	v_mfma_f32_16x16x32_bf16 v[0:3], v[208:211], v[232:235], v[172:175]
	v_mfma_f32_16x16x32_bf16 v[0:3], v[224:227], v[236:239], v[0:3]
	s_setprio 0
	s_barrier
	s_andn2_b64 vcc, exec, s[18:19]
	s_cbranch_vccnz .LBB0_667
	s_barrier

; #define PG8_STAGE(bufoff, gbase, voff) do { _Pragma("unroll") for (int _i = 0; _i < 2; ++_i) \
;         __builtin_amdgcn_global_load_lds((const unsigned*)((const char*)(gbase) + (voff)[_i]), (LAS unsigned*)(lds + (bufoff) + ldsw + _i * 8192), 16, 0, 0); } while (0)
; #define PG8_LDA(dst, b, h) do { _Pragma("unroll") for (int m = 0; m < 4; ++m) _Pragma("unroll") for (int k = 0; k < 2; ++k) dst[m][k] = *(const LAS bf16x8*)(lds + PG8_SA(b, h) + aoff + m * 2048 + k * 1024); } while (0)
; #define PG8_LDB(dst, b, h) do { _Pragma("unroll") for (int n = 0; n < 2; ++n) _Pragma("unroll") for (int k = 0; k < 2; ++k) dst[n][k] = *(const LAS bf16x8*)(lds + PG8_SB(b, h) + boff + n * 2048 + k * 1024); } while (0)
; #define PG8_MMA(ai, bj, At, Bt) do { __builtin_amdgcn_s_setprio(1); _Pragma("unroll") for (int m = 0; m < 4; ++m) _Pragma("unroll") for (int n = 0; n < 2; ++n) _Pragma("unroll") for (int k = 0; k < 2; ++k) \
;         acc[ai][bj][m][n] = __builtin_amdgcn_mfma_f32_16x16x32_bf16(Bt[n][k], At[m][k], acc[ai][bj][m][n], 0, 0, 0); __builtin_amdgcn_s_setprio(0); } while (0)
; template <class Epi, bool ALIGN_EPI, int K, int LDA, int LDB>
; __device__ __forceinline__ void gemm_phase(LAS unsigned char* lds, const int wid, const Gemm g, const StaticOrder& S, const Epi& E) {
;     ...
;         const bool has_next = S.next(ui + 1, nxt);
;         const char* nA = has_next ? (const char*)g.A + (size_t)nxt.pm * tA : cA; const char* nB = has_next ? (const char*)g.Bt + (size_t)nxt.pn * tB : cB;
;         for (int t = 0; t < nt; t += 2) {
;             const bool last = (t == nt - 2);
;             const char* a1 = cA + (size_t)(t + 1) * kstep;
;             const char* a2 = last ? nA : cA + (size_t)(t + 2) * kstep; const char* b2 = last ? nB : cB + (size_t)(t + 2) * kstep;
;             const char* a3 = a2 + kstep; const char* b3 = b2 + kstep;
;             PG8_LDB(B0, 0, 0); PG8_LDB(B1, 0, 1); PG8_SCHED; PG8_LDA(At, 0, 0); PG8_STAGE(PG8_SA(1, 1), a1 + hA, voffA);
;             PG8_WAIT_V(8); PG8_WAIT_L(0); PG8_BAR; PG8_MMA(0, 0, At, B0); PG8_MMA(0, 1, At, B1); PG8_BAR; PG8_SCHED;
;             PG8_LDA(At, 0, 1); PG8_STAGE(PG8_SB(0, 0), b2, voffB); PG8_STAGE(PG8_SB(0, 1), b2 + hB, voffB); PG8_STAGE(PG8_SA(0, 0), a2, voffA);
;             PG8_WAIT_V(8); PG8_WAIT_L(0); PG8_BAR; PG8_MMA(1, 0, At, B0); PG8_MMA(1, 1, At, B1); PG8_BAR; PG8_SCHED;
.LBB0_689:
	ds_read_b128 v[0:3], v145
	ds_read_b128 v[4:7], v145 offset:1024
	ds_read_b128 v[8:11], v145 offset:2048
	ds_read_b128 v[12:15], v145 offset:3072
	ds_read_b128 v[16:19], v147
	ds_read_b128 v[20:23], v147 offset:1024
	ds_read_b128 v[24:27], v147 offset:2048
	ds_read_b128 v[28:31], v147 offset:3072
	s_ashr_i32 s31, s30, 31
	s_lshl_b64 s[36:37], s[30:31], 17
	s_add_u32 s36, s51, s36
	s_addc_u32 s37, s54, s37
	s_and_b64 s[8:9], s[8:9], exec
	s_cselect_b32 s9, s37, s41
	s_cselect_b32 s8, s36, s40
	s_add_u32 s66, s38, 0xa0080
	s_addc_u32 s67, s39, 0
	s_add_i32 s70, s55, 0xc000
	v_lshl_add_u64 v[64:65], s[66:67], 0, v[128:129]
	s_mov_b32 m0, s70
	s_add_i32 s31, s55, 0xe000
	ds_read_b128 v[32:35], v149
	ds_read_b128 v[36:39], v149 offset:1024
	ds_read_b128 v[40:43], v149 offset:2048
	ds_read_b128 v[44:47], v149 offset:3072
	ds_read_b128 v[48:51], v149 offset:4096
	ds_read_b128 v[52:55], v149 offset:5120
	ds_read_b128 v[56:59], v149 offset:6144
	ds_read_b128 v[60:63], v149 offset:7168
	global_load_lds_dwordx4 v[64:65], off
	v_lshl_add_u64 v[64:65], s[66:67], 0, v[132:133]
	s_mov_b32 m0, s31
	s_nop 0
	global_load_lds_dwordx4 v[64:65], off
	s_waitcnt vmcnt(8)
	s_waitcnt lgkmcnt(0)
	s_barrier
	s_setprio 1
	s_waitcnt lgkmcnt(0)
	v_mfma_f32_16x16x32_bf16 v[64:67], v[0:3], v[32:35], 0
	v_mfma_f32_16x16x32_bf16 v[68:71], v[8:11], v[32:35], 0
	v_mfma_f32_16x16x32_bf16 v[72:75], v[0:3], v[40:43], 0
	v_mfma_f32_16x16x32_bf16 v[76:79], v[8:11], v[40:43], 0
	v_mfma_f32_16x16x32_bf16 v[80:83], v[0:3], v[48:51], 0
	v_mfma_f32_16x16x32_bf16 v[84:87], v[8:11], v[48:51], 0
	v_mfma_f32_16x16x32_bf16 v[88:91], v[0:3], v[56:59], 0
	v_mfma_f32_16x16x32_bf16 v[92:95], v[8:11], v[56:59], 0
	v_mfma_f32_16x16x32_bf16 v[64:67], v[4:7], v[36:39], v[64:67]
	v_mfma_f32_16x16x32_bf16 v[68:71], v[12:15], v[36:39], v[68:71]
	v_mfma_f32_16x16x32_bf16 v[72:75], v[4:7], v[44:47], v[72:75]
	v_mfma_f32_16x16x32_bf16 v[76:79], v[12:15], v[44:47], v[76:79]
	v_mfma_f32_16x16x32_bf16 v[80:83], v[4:7], v[52:55], v[80:83]
	v_mfma_f32_16x16x32_bf16 v[84:87], v[12:15], v[52:55], v[84:87]
	v_mfma_f32_16x16x32_bf16 v[88:91], v[4:7], v[60:63], v[88:91]
	v_mfma_f32_16x16x32_bf16 v[92:95], v[12:15], v[60:63], v[92:95]
	v_mfma_f32_16x16x32_bf16 v[96:99], v[16:19], v[32:35], 0
	v_mfma_f32_16x16x32_bf16 v[32:35], v[24:27], v[32:35], 0
	v_mfma_f32_16x16x32_bf16 v[96:99], v[20:23], v[36:39], v[96:99]
	v_mfma_f32_16x16x32_bf16 v[32:35], v[28:31], v[36:39], v[32:35]
	v_mfma_f32_16x16x32_bf16 v[36:39], v[16:19], v[40:43], 0
	v_mfma_f32_16x16x32_bf16 v[40:43], v[24:27], v[40:43], 0
	v_mfma_f32_16x16x32_bf16 v[36:39], v[20:23], v[44:47], v[36:39]
	v_mfma_f32_16x16x32_bf16 v[40:43], v[28:31], v[44:47], v[40:43]
	v_mfma_f32_16x16x32_bf16 v[44:47], v[16:19], v[48:51], 0
	v_mfma_f32_16x16x32_bf16 v[48:51], v[24:27], v[48:51], 0
	v_mfma_f32_16x16x32_bf16 v[44:47], v[20:23], v[52:55], v[44:47]
	v_mfma_f32_16x16x32_bf16 v[48:51], v[28:31], v[52:55], v[48:51]
	v_mfma_f32_16x16x32_bf16 v[52:55], v[16:19], v[56:59], 0
	v_mfma_f32_16x16x32_bf16 v[56:59], v[24:27], v[56:59], 0
	v_mfma_f32_16x16x32_bf16 v[52:55], v[20:23], v[60:63], v[52:55]
	v_mfma_f32_16x16x32_bf16 v[56:59], v[28:31], v[60:63], v[56:59]
	s_setprio 0
	s_barrier
	s_add_i32 s68, s43, s0
	v_lshl_add_u64 v[140:141], s[40:41], 0, v[130:131]
	s_add_i32 s65, s68, 0x2000
	v_lshl_add_u64 v[150:151], v[140:141], 0, s[24:25]
	s_mov_b32 m0, s68
	v_lshl_add_u64 v[214:215], s[40:41], 0, v[134:135]
	s_add_u32 s72, s40, 0x10100
	ds_read_b128 v[60:63], v149 offset:16384
	ds_read_b128 v[100:103], v149 offset:17408
	ds_read_b128 v[104:107], v149 offset:18432
	ds_read_b128 v[108:111], v149 offset:19456
	ds_read_b128 v[112:115], v149 offset:20480
	ds_read_b128 v[116:119], v149 offset:21504
	ds_read_b128 v[120:123], v149 offset:22528
	ds_read_b128 v[124:127], v149 offset:23552
	global_load_lds_dwordx4 v[150:151], off
	v_lshl_add_u64 v[150:151], v[214:215], 0, s[24:25]
	s_mov_b32 m0, s65
	s_addc_u32 s73, s41, 0
	s_add_i32 s66, s61, s0
	global_load_lds_dwordx4 v[150:151], off
	v_lshl_add_u64 v[150:151], s[72:73], 0, v[130:131]
	s_mov_b32 m0, s66
	s_add_i32 s67, s66, 0x2000
	global_load_lds_dwordx4 v[150:151], off
	v_lshl_add_u64 v[150:151], s[72:73], 0, v[134:135]
	s_mov_b32 m0, s67
	v_lshl_add_u64 v[216:217], s[38:39], 0, v[128:129]
	global_load_lds_dwordx4 v[150:151], off
	v_lshl_add_u64 v[150:151], v[216:217], 0, s[24:25]
	s_mov_b32 m0, s55
	v_lshl_add_u64 v[218:219], s[38:39], 0, v[132:133]
	global_load_lds_dwordx4 v[150:151], off
	v_lshl_add_u64 v[150:151], v[218:219], 0, s[24:25]
	s_mov_b32 m0, s56
	s_nop 0
	global_load_lds_dwordx4 v[150:151], off
	s_waitcnt vmcnt(8)
	s_waitcnt lgkmcnt(0)
	s_barrier
; #define PG8_STAGE(bufoff, gbase, voff) do { _Pragma("unroll") for (int _i = 0; _i < 2; ++_i) \
;         __builtin_amdgcn_global_load_lds((const unsigned*)((const char*)(gbase) + (voff)[_i]), (LAS unsigned*)(lds + (bufoff) + ldsw + _i * 8192), 16, 0, 0); } while (0)
; #define PG8_LDA(dst, b, h) do { _Pragma("unroll") for (int m = 0; m < 4; ++m) _Pragma("unroll") for (int k = 0; k < 2; ++k) dst[m][k] = *(const LAS bf16x8*)(lds + PG8_SA(b, h) + aoff + m * 2048 + k * 1024); } while (0)
; #define PG8_LDB(dst, b, h) do { _Pragma("unroll") for (int n = 0; n < 2; ++n) _Pragma("unroll") for (int k = 0; k < 2; ++k) dst[n][k] = *(const LAS bf16x8*)(lds + PG8_SB(b, h) + boff + n * 2048 + k * 1024); } while (0)
; #define PG8_MMA(ai, bj, At, Bt) do { __builtin_amdgcn_s_setprio(1); _Pragma("unroll") for (int m = 0; m < 4; ++m) _Pragma("unroll") for (int n = 0; n < 2; ++n) _Pragma("unroll") for (int k = 0; k < 2; ++k) \
;         acc[ai][bj][m][n] = __builtin_amdgcn_mfma_f32_16x16x32_bf16(Bt[n][k], At[m][k], acc[ai][bj][m][n], 0, 0, 0); __builtin_amdgcn_s_setprio(0); } while (0)
; #define PG8_WAIT_V(n) asm volatile("s_waitcnt vmcnt(" #n ")" ::: "memory")
; #define PG8_WAIT_L(n) asm volatile("s_waitcnt lgkmcnt(" #n ")" ::: "memory")
; #define PG8_BAR __builtin_amdgcn_s_barrier()
; #define PG8_SCHED __builtin_amdgcn_sched_barrier(0)
; template <class Epi, bool ALIGN_EPI, int K, int LDA, int LDB>
; __device__ __forceinline__ void gemm_phase(LAS unsigned char* lds, const int wid, const Gemm g, const StaticOrder& S, const Epi& E) {
;     ...
;             PG8_WAIT_V(8); PG8_WAIT_L(0); PG8_BAR; PG8_MMA(1, 0, At, B0); PG8_MMA(1, 1, At, B1); PG8_BAR; PG8_SCHED;
;             PG8_LDB(B0, 1, 0); PG8_LDB(B1, 1, 1); PG8_SCHED; PG8_LDA(At, 1, 0); PG8_STAGE(PG8_SA(0, 1), a2 + hA, voffA);
;             PG8_WAIT_V(8); PG8_WAIT_L(0); PG8_BAR; PG8_MMA(0, 0, At, B0); PG8_MMA(0, 1, At, B1); PG8_BAR; PG8_SCHED;
	s_setprio 1
	s_waitcnt lgkmcnt(0)
	v_mfma_f32_16x16x32_bf16 v[150:153], v[0:3], v[60:63], 0
	v_mfma_f32_16x16x32_bf16 v[158:161], v[0:3], v[104:107], 0
	v_mfma_f32_16x16x32_bf16 v[166:169], v[0:3], v[112:115], 0
	v_mfma_f32_16x16x32_bf16 v[0:3], v[0:3], v[120:123], 0
	v_mfma_f32_16x16x32_bf16 v[150:153], v[4:7], v[100:103], v[150:153]
	v_mfma_f32_16x16x32_bf16 v[158:161], v[4:7], v[108:111], v[158:161]
	v_mfma_f32_16x16x32_bf16 v[166:169], v[4:7], v[116:119], v[166:169]
	v_mfma_f32_16x16x32_bf16 v[0:3], v[4:7], v[124:127], v[0:3]
	v_mfma_f32_16x16x32_bf16 v[4:7], v[8:11], v[120:123], 0
	v_mfma_f32_16x16x32_bf16 v[154:157], v[8:11], v[60:63], 0
	v_mfma_f32_16x16x32_bf16 v[162:165], v[8:11], v[104:107], 0
	v_mfma_f32_16x16x32_bf16 v[170:173], v[8:11], v[112:115], 0
	v_mfma_f32_16x16x32_bf16 v[4:7], v[12:15], v[124:127], v[4:7]
	v_mfma_f32_16x16x32_bf16 v[154:157], v[12:15], v[100:103], v[154:157]
	v_mfma_f32_16x16x32_bf16 v[162:165], v[12:15], v[108:111], v[162:165]
	v_mfma_f32_16x16x32_bf16 v[170:173], v[12:15], v[116:119], v[170:173]
	v_mfma_f32_16x16x32_bf16 v[8:11], v[16:19], v[60:63], 0
	v_mfma_f32_16x16x32_bf16 v[12:15], v[24:27], v[60:63], 0
	v_mfma_f32_16x16x32_bf16 v[8:11], v[20:23], v[100:103], v[8:11]
	v_mfma_f32_16x16x32_bf16 v[12:15], v[28:31], v[100:103], v[12:15]
	v_mfma_f32_16x16x32_bf16 v[60:63], v[16:19], v[104:107], 0
	v_mfma_f32_16x16x32_bf16 v[100:103], v[24:27], v[104:107], 0
	v_mfma_f32_16x16x32_bf16 v[104:107], v[16:19], v[112:115], 0
	v_mfma_f32_16x16x32_bf16 v[16:19], v[16:19], v[120:123], 0
	v_mfma_f32_16x16x32_bf16 v[60:63], v[20:23], v[108:111], v[60:63]
	v_mfma_f32_16x16x32_bf16 v[100:103], v[28:31], v[108:111], v[100:103]
	v_mfma_f32_16x16x32_bf16 v[104:107], v[20:23], v[116:119], v[104:107]
	v_mfma_f32_16x16x32_bf16 v[108:111], v[24:27], v[112:115], 0
	v_mfma_f32_16x16x32_bf16 v[16:19], v[20:23], v[124:127], v[16:19]
	v_mfma_f32_16x16x32_bf16 v[20:23], v[24:27], v[120:123], 0
	v_mfma_f32_16x16x32_bf16 v[108:111], v[28:31], v[116:119], v[108:111]
	v_mfma_f32_16x16x32_bf16 v[20:23], v[28:31], v[124:127], v[20:23]
	s_setprio 0
	s_barrier
	s_add_i32 s71, 0, 0x18000
	s_add_i32 s74, 0, 0x1c000
	v_add_u32_e32 v142, s71, v143
	v_add_u32_e32 v144, s74, v143
	ds_read_b128 v[24:27], v142
	ds_read_b128 v[28:31], v142 offset:1024
	ds_read_b128 v[112:115], v142 offset:2048
	ds_read_b128 v[116:119], v142 offset:3072
	ds_read_b128 v[120:123], v144
	ds_read_b128 v[124:127], v144 offset:1024
	ds_read_b128 v[174:177], v144 offset:2048
	ds_read_b128 v[178:181], v144 offset:3072
	s_add_u32 s72, s38, 0xa0100
	s_addc_u32 s73, s39, 0
	s_mov_b32 m0, s57
	v_lshl_add_u64 v[220:221], s[72:73], 0, v[128:129]
	ds_read_b128 v[182:185], v149 offset:32768
	ds_read_b128 v[186:189], v149 offset:33792
	ds_read_b128 v[190:193], v149 offset:34816
	ds_read_b128 v[194:197], v149 offset:35840
	ds_read_b128 v[198:201], v149 offset:36864
	ds_read_b128 v[202:205], v149 offset:37888
	ds_read_b128 v[206:209], v149 offset:38912
	ds_read_b128 v[210:213], v149 offset:39936
	global_load_lds_dwordx4 v[220:221], off
	v_lshl_add_u64 v[220:221], s[72:73], 0, v[132:133]
	s_mov_b32 m0, s58
	s_nop 0
	global_load_lds_dwordx4 v[220:221], off
	s_waitcnt vmcnt(8)
	s_waitcnt lgkmcnt(0)
	s_barrier
	s_setprio 1
	s_waitcnt lgkmcnt(0)
	v_mfma_f32_16x16x32_bf16 v[64:67], v[24:27], v[182:185], v[64:67]
	v_mfma_f32_16x16x32_bf16 v[68:71], v[112:115], v[182:185], v[68:71]
	v_mfma_f32_16x16x32_bf16 v[72:75], v[24:27], v[190:193], v[72:75]
	v_mfma_f32_16x16x32_bf16 v[76:79], v[112:115], v[190:193], v[76:79]
	v_mfma_f32_16x16x32_bf16 v[80:83], v[24:27], v[198:201], v[80:83]
	v_mfma_f32_16x16x32_bf16 v[84:87], v[112:115], v[198:201], v[84:87]
	v_mfma_f32_16x16x32_bf16 v[88:91], v[24:27], v[206:209], v[88:91]
	v_mfma_f32_16x16x32_bf16 v[92:95], v[112:115], v[206:209], v[92:95]
	v_mfma_f32_16x16x32_bf16 v[64:67], v[28:31], v[186:189], v[64:67]
	v_mfma_f32_16x16x32_bf16 v[68:71], v[116:119], v[186:189], v[68:71]
	v_mfma_f32_16x16x32_bf16 v[72:75], v[28:31], v[194:197], v[72:75]
	v_mfma_f32_16x16x32_bf16 v[76:79], v[116:119], v[194:197], v[76:79]
	v_mfma_f32_16x16x32_bf16 v[80:83], v[28:31], v[202:205], v[80:83]
	v_mfma_f32_16x16x32_bf16 v[84:87], v[116:119], v[202:205], v[84:87]
	v_mfma_f32_16x16x32_bf16 v[88:91], v[28:31], v[210:213], v[88:91]
	v_mfma_f32_16x16x32_bf16 v[92:95], v[116:119], v[210:213], v[92:95]
	v_mfma_f32_16x16x32_bf16 v[96:99], v[120:123], v[182:185], v[96:99]
	v_mfma_f32_16x16x32_bf16 v[32:35], v[174:177], v[182:185], v[32:35]
	v_mfma_f32_16x16x32_bf16 v[36:39], v[120:123], v[190:193], v[36:39]
	v_mfma_f32_16x16x32_bf16 v[40:43], v[174:177], v[190:193], v[40:43]
	v_mfma_f32_16x16x32_bf16 v[44:47], v[120:123], v[198:201], v[44:47]
	v_mfma_f32_16x16x32_bf16 v[48:51], v[174:177], v[198:201], v[48:51]
	v_mfma_f32_16x16x32_bf16 v[52:55], v[120:123], v[206:209], v[52:55]
	v_mfma_f32_16x16x32_bf16 v[56:59], v[174:177], v[206:209], v[56:59]
	v_mfma_f32_16x16x32_bf16 v[96:99], v[124:127], v[186:189], v[96:99]
	v_mfma_f32_16x16x32_bf16 v[32:35], v[178:181], v[186:189], v[32:35]
	v_mfma_f32_16x16x32_bf16 v[36:39], v[124:127], v[194:197], v[36:39]
	v_mfma_f32_16x16x32_bf16 v[40:43], v[178:181], v[194:197], v[40:43]
	v_mfma_f32_16x16x32_bf16 v[44:47], v[124:127], v[202:205], v[44:47]
	v_mfma_f32_16x16x32_bf16 v[48:51], v[178:181], v[202:205], v[48:51]
	v_mfma_f32_16x16x32_bf16 v[52:55], v[124:127], v[210:213], v[52:55]
	v_mfma_f32_16x16x32_bf16 v[56:59], v[178:181], v[210:213], v[56:59]
	s_setprio 0
	s_barrier
; #define PG8_STAGE(bufoff, gbase, voff) do { _Pragma("unroll") for (int _i = 0; _i < 2; ++_i) \
;         __builtin_amdgcn_global_load_lds((const unsigned*)((const char*)(gbase) + (voff)[_i]), (LAS unsigned*)(lds + (bufoff) + ldsw + _i * 8192), 16, 0, 0); } while (0)
; #define PG8_LDA(dst, b, h) do { _Pragma("unroll") for (int m = 0; m < 4; ++m) _Pragma("unroll") for (int k = 0; k < 2; ++k) dst[m][k] = *(const LAS bf16x8*)(lds + PG8_SA(b, h) + aoff + m * 2048 + k * 1024); } while (0)
; #define PG8_LDB(dst, b, h) do { _Pragma("unroll") for (int n = 0; n < 2; ++n) _Pragma("unroll") for (int k = 0; k < 2; ++k) dst[n][k] = *(const LAS bf16x8*)(lds + PG8_SB(b, h) + boff + n * 2048 + k * 1024); } while (0)
; #define PG8_MMA(ai, bj, At, Bt) do { __builtin_amdgcn_s_setprio(1); _Pragma("unroll") for (int m = 0; m < 4; ++m) _Pragma("unroll") for (int n = 0; n < 2; ++n) _Pragma("unroll") for (int k = 0; k < 2; ++k) \
;         acc[ai][bj][m][n] = __builtin_amdgcn_mfma_f32_16x16x32_bf16(Bt[n][k], At[m][k], acc[ai][bj][m][n], 0, 0, 0); __builtin_amdgcn_s_setprio(0); } while (0)
; #define PG8_WAIT_V(n) asm volatile("s_waitcnt vmcnt(" #n ")" ::: "memory")
; #define PG8_WAIT_L(n) asm volatile("s_waitcnt lgkmcnt(" #n ")" ::: "memory")
; #define PG8_BAR __builtin_amdgcn_s_barrier()
; #define PG8_SCHED __builtin_amdgcn_sched_barrier(0)
; template <class Epi, bool ALIGN_EPI, int K, int LDA, int LDB>
; __device__ __forceinline__ void gemm_phase(LAS unsigned char* lds, const int wid, const Gemm g, const StaticOrder& S, const Epi& E) {
;     ...
;             PG8_LDB(B0, 0, 0); PG8_LDB(B1, 0, 1); PG8_SCHED; PG8_LDA(At, 0, 0); PG8_STAGE(PG8_SA(1, 1), a1 + hA, voffA);
;             PG8_WAIT_V(8); PG8_WAIT_L(0); PG8_BAR; PG8_MMA(0, 0, At, B0); PG8_MMA(0, 1, At, B1); PG8_BAR; PG8_SCHED;
;     ...
;             PG8_LDA(At, 1, 1); PG8_STAGE(PG8_SB(1, 0), b3, voffB); PG8_STAGE(PG8_SB(1, 1), b3 + hB, voffB); PG8_STAGE(PG8_SA(1, 0), a3, voffA);
;             PG8_WAIT_V(8); PG8_WAIT_L(0); PG8_BAR; PG8_MMA(1, 0, At, B0); PG8_MMA(1, 1, At, B1); PG8_BAR; PG8_SCHED;
	s_add_i32 s71, s71, s0
	s_add_i32 s69, s71, 0x2000
	v_lshl_add_u64 v[140:141], v[140:141], 0, s[26:27]
	s_mov_b32 m0, s71
	s_add_u32 s72, s40, 0x10180
	ds_read_b128 v[182:185], v149 offset:49152
	ds_read_b128 v[186:189], v149 offset:50176
	ds_read_b128 v[190:193], v149 offset:51200
	ds_read_b128 v[194:197], v149 offset:52224
	ds_read_b128 v[198:201], v149 offset:53248
	ds_read_b128 v[202:205], v149 offset:54272
	ds_read_b128 v[206:209], v149 offset:55296
	ds_read_b128 v[210:213], v149 offset:56320
	global_load_lds_dwordx4 v[140:141], off
	v_lshl_add_u64 v[140:141], v[214:215], 0, s[26:27]
	s_mov_b32 m0, s69
	s_addc_u32 s73, s41, 0
	s_add_i32 s40, s74, s0
	global_load_lds_dwordx4 v[140:141], off
	v_lshl_add_u64 v[140:141], s[72:73], 0, v[130:131]
	s_mov_b32 m0, s40
	s_add_i32 s41, s40, 0x2000
	global_load_lds_dwordx4 v[140:141], off
	v_lshl_add_u64 v[140:141], s[72:73], 0, v[134:135]
	s_mov_b32 m0, s41
	s_nop 0
	global_load_lds_dwordx4 v[140:141], off
	v_lshl_add_u64 v[140:141], v[216:217], 0, s[26:27]
	s_mov_b32 m0, s59
	s_nop 0
	global_load_lds_dwordx4 v[140:141], off
	v_lshl_add_u64 v[140:141], v[218:219], 0, s[26:27]
	s_mov_b32 m0, s60
	s_nop 0
	global_load_lds_dwordx4 v[140:141], off
	s_waitcnt vmcnt(8)
	s_waitcnt lgkmcnt(0)
	s_barrier
	s_setprio 1
	s_waitcnt lgkmcnt(0)
	v_mfma_f32_16x16x32_bf16 v[0:3], v[24:27], v[206:209], v[0:3]
	v_mfma_f32_16x16x32_bf16 v[4:7], v[112:115], v[206:209], v[4:7]
	v_mfma_f32_16x16x32_bf16 v[150:153], v[24:27], v[182:185], v[150:153]
	v_mfma_f32_16x16x32_bf16 v[154:157], v[112:115], v[182:185], v[154:157]
	v_mfma_f32_16x16x32_bf16 v[158:161], v[24:27], v[190:193], v[158:161]
	v_mfma_f32_16x16x32_bf16 v[162:165], v[112:115], v[190:193], v[162:165]
	v_mfma_f32_16x16x32_bf16 v[166:169], v[24:27], v[198:201], v[166:169]
	v_mfma_f32_16x16x32_bf16 v[170:173], v[112:115], v[198:201], v[170:173]
	v_mfma_f32_16x16x32_bf16 v[0:3], v[28:31], v[210:213], v[0:3]
	v_mfma_f32_16x16x32_bf16 v[4:7], v[116:119], v[210:213], v[4:7]
	v_mfma_f32_16x16x32_bf16 v[150:153], v[28:31], v[186:189], v[150:153]
	v_mfma_f32_16x16x32_bf16 v[154:157], v[116:119], v[186:189], v[154:157]
	v_mfma_f32_16x16x32_bf16 v[158:161], v[28:31], v[194:197], v[158:161]
	v_mfma_f32_16x16x32_bf16 v[162:165], v[116:119], v[194:197], v[162:165]
	v_mfma_f32_16x16x32_bf16 v[166:169], v[28:31], v[202:205], v[166:169]
	v_mfma_f32_16x16x32_bf16 v[170:173], v[116:119], v[202:205], v[170:173]
	v_mfma_f32_16x16x32_bf16 v[8:11], v[120:123], v[182:185], v[8:11]
	v_mfma_f32_16x16x32_bf16 v[12:15], v[174:177], v[182:185], v[12:15]
	v_mfma_f32_16x16x32_bf16 v[24:27], v[120:123], v[190:193], v[60:63]
	v_mfma_f32_16x16x32_bf16 v[28:31], v[174:177], v[190:193], v[100:103]
	v_mfma_f32_16x16x32_bf16 v[60:63], v[120:123], v[198:201], v[104:107]
	v_mfma_f32_16x16x32_bf16 v[100:103], v[174:177], v[198:201], v[108:111]
	v_mfma_f32_16x16x32_bf16 v[16:19], v[120:123], v[206:209], v[16:19]
	v_mfma_f32_16x16x32_bf16 v[20:23], v[174:177], v[206:209], v[20:23]
	v_mfma_f32_16x16x32_bf16 v[8:11], v[124:127], v[186:189], v[8:11]
	v_mfma_f32_16x16x32_bf16 v[12:15], v[178:181], v[186:189], v[12:15]
	v_mfma_f32_16x16x32_bf16 v[24:27], v[124:127], v[194:197], v[24:27]
	v_mfma_f32_16x16x32_bf16 v[28:31], v[178:181], v[194:197], v[28:31]
	v_mfma_f32_16x16x32_bf16 v[60:63], v[124:127], v[202:205], v[60:63]
	v_mfma_f32_16x16x32_bf16 v[100:103], v[178:181], v[202:205], v[100:103]
	v_mfma_f32_16x16x32_bf16 v[16:19], v[124:127], v[210:213], v[16:19]
	v_mfma_f32_16x16x32_bf16 v[20:23], v[178:181], v[210:213], v[20:23]
	s_setprio 0
	s_barrier
	ds_read_b128 v[104:107], v145
	ds_read_b128 v[108:111], v145 offset:1024
	ds_read_b128 v[112:115], v145 offset:2048
	ds_read_b128 v[116:119], v145 offset:3072
	ds_read_b128 v[120:123], v147
	ds_read_b128 v[124:127], v147 offset:1024
	ds_read_b128 v[174:177], v147 offset:2048
	ds_read_b128 v[178:181], v147 offset:3072
	s_add_u32 s38, s38, 0xa0180
	s_addc_u32 s39, s39, 0
	s_mov_b32 m0, s70
	v_lshl_add_u64 v[140:141], s[38:39], 0, v[128:129]
	ds_read_b128 v[182:185], v149
	ds_read_b128 v[186:189], v149 offset:1024
	ds_read_b128 v[190:193], v149 offset:2048
	ds_read_b128 v[194:197], v149 offset:3072
	ds_read_b128 v[198:201], v149 offset:4096
	ds_read_b128 v[202:205], v149 offset:5120
	ds_read_b128 v[206:209], v149 offset:6144
	ds_read_b128 v[210:213], v149 offset:7168
	global_load_lds_dwordx4 v[140:141], off
	v_lshl_add_u64 v[140:141], s[38:39], 0, v[132:133]
	s_mov_b32 m0, s31
	s_nop 0
	global_load_lds_dwordx4 v[140:141], off
	s_waitcnt vmcnt(8)
	s_waitcnt lgkmcnt(0)
	s_barrier
; #define PG8_STAGE(bufoff, gbase, voff) do { _Pragma("unroll") for (int _i = 0; _i < 2; ++_i) \
;         __builtin_amdgcn_global_load_lds((const unsigned*)((const char*)(gbase) + (voff)[_i]), (LAS unsigned*)(lds + (bufoff) + ldsw + _i * 8192), 16, 0, 0); } while (0)
; #define PG8_LDA(dst, b, h) do { _Pragma("unroll") for (int m = 0; m < 4; ++m) _Pragma("unroll") for (int k = 0; k < 2; ++k) dst[m][k] = *(const LAS bf16x8*)(lds + PG8_SA(b, h) + aoff + m * 2048 + k * 1024); } while (0)
; #define PG8_LDB(dst, b, h) do { _Pragma("unroll") for (int n = 0; n < 2; ++n) _Pragma("unroll") for (int k = 0; k < 2; ++k) dst[n][k] = *(const LAS bf16x8*)(lds + PG8_SB(b, h) + boff + n * 2048 + k * 1024); } while (0)
; #define PG8_MMA(ai, bj, At, Bt) do { __builtin_amdgcn_s_setprio(1); _Pragma("unroll") for (int m = 0; m < 4; ++m) _Pragma("unroll") for (int n = 0; n < 2; ++n) _Pragma("unroll") for (int k = 0; k < 2; ++k) \
;         acc[ai][bj][m][n] = __builtin_amdgcn_mfma_f32_16x16x32_bf16(Bt[n][k], At[m][k], acc[ai][bj][m][n], 0, 0, 0); __builtin_amdgcn_s_setprio(0); } while (0)
; #define PG8_WAIT_V(n) asm volatile("s_waitcnt vmcnt(" #n ")" ::: "memory")
; #define PG8_WAIT_L(n) asm volatile("s_waitcnt lgkmcnt(" #n ")" ::: "memory")
; #define PG8_BAR __builtin_amdgcn_s_barrier()
; #define PG8_SCHED __builtin_amdgcn_sched_barrier(0)
; template <class Epi, bool ALIGN_EPI, int K, int LDA, int LDB>
; __device__ __forceinline__ void gemm_phase(LAS unsigned char* lds, const int wid, const Gemm g, const StaticOrder& S, const Epi& E) {
;     ...
;             PG8_WAIT_V(8); PG8_WAIT_L(0); PG8_BAR; PG8_MMA(0, 0, At, B0); PG8_MMA(0, 1, At, B1); PG8_BAR; PG8_SCHED;
;             PG8_LDA(At, 0, 1); PG8_STAGE(PG8_SB(0, 0), b2, voffB); PG8_STAGE(PG8_SB(0, 1), b2 + hB, voffB); PG8_STAGE(PG8_SA(0, 0), a2, voffA);
;             PG8_WAIT_V(8); PG8_WAIT_L(0); PG8_BAR; PG8_MMA(1, 0, At, B0); PG8_MMA(1, 1, At, B1); PG8_BAR; PG8_SCHED;
;             PG8_LDB(B0, 1, 0); PG8_LDB(B1, 1, 1); PG8_SCHED; PG8_LDA(At, 1, 0); PG8_STAGE(PG8_SA(0, 1), a2 + hA, voffA);
;             PG8_WAIT_V(8); PG8_WAIT_L(0); PG8_BAR; PG8_MMA(0, 0, At, B0); PG8_MMA(0, 1, At, B1); PG8_BAR; PG8_SCHED;
;             PG8_LDA(At, 1, 1); PG8_STAGE(PG8_SB(1, 0), b3, voffB); PG8_STAGE(PG8_SB(1, 1), b3 + hB, voffB); PG8_STAGE(PG8_SA(1, 0), a3, voffA);
	s_setprio 1
	s_waitcnt lgkmcnt(0)
	v_mfma_f32_16x16x32_bf16 v[64:67], v[104:107], v[182:185], v[64:67]
	v_mfma_f32_16x16x32_bf16 v[68:71], v[112:115], v[182:185], v[68:71]
	v_mfma_f32_16x16x32_bf16 v[72:75], v[104:107], v[190:193], v[72:75]
	v_mfma_f32_16x16x32_bf16 v[76:79], v[112:115], v[190:193], v[76:79]
	v_mfma_f32_16x16x32_bf16 v[80:83], v[104:107], v[198:201], v[80:83]
	v_mfma_f32_16x16x32_bf16 v[84:87], v[112:115], v[198:201], v[84:87]
	v_mfma_f32_16x16x32_bf16 v[88:91], v[104:107], v[206:209], v[88:91]
	v_mfma_f32_16x16x32_bf16 v[64:67], v[108:111], v[186:189], v[64:67]
	v_mfma_f32_16x16x32_bf16 v[68:71], v[116:119], v[186:189], v[68:71]
	v_mfma_f32_16x16x32_bf16 v[72:75], v[108:111], v[194:197], v[72:75]
	v_mfma_f32_16x16x32_bf16 v[76:79], v[116:119], v[194:197], v[76:79]
	v_mfma_f32_16x16x32_bf16 v[80:83], v[108:111], v[202:205], v[80:83]
	v_mfma_f32_16x16x32_bf16 v[84:87], v[116:119], v[202:205], v[84:87]
	v_mfma_f32_16x16x32_bf16 v[214:217], v[108:111], v[210:213], v[88:91]
	v_mfma_f32_16x16x32_bf16 v[88:91], v[112:115], v[206:209], v[92:95]
	v_mfma_f32_16x16x32_bf16 v[218:221], v[116:119], v[210:213], v[88:91]
	v_mfma_f32_16x16x32_bf16 v[88:91], v[120:123], v[182:185], v[96:99]
	v_mfma_f32_16x16x32_bf16 v[32:35], v[174:177], v[182:185], v[32:35]
	v_mfma_f32_16x16x32_bf16 v[36:39], v[120:123], v[190:193], v[36:39]
	v_mfma_f32_16x16x32_bf16 v[40:43], v[174:177], v[190:193], v[40:43]
	v_mfma_f32_16x16x32_bf16 v[44:47], v[120:123], v[198:201], v[44:47]
	v_mfma_f32_16x16x32_bf16 v[48:51], v[174:177], v[198:201], v[48:51]
	v_mfma_f32_16x16x32_bf16 v[52:55], v[120:123], v[206:209], v[52:55]
	v_mfma_f32_16x16x32_bf16 v[56:59], v[174:177], v[206:209], v[56:59]
	v_mfma_f32_16x16x32_bf16 v[96:99], v[124:127], v[186:189], v[88:91]
	v_mfma_f32_16x16x32_bf16 v[32:35], v[178:181], v[186:189], v[32:35]
	v_mfma_f32_16x16x32_bf16 v[36:39], v[124:127], v[194:197], v[36:39]
	v_mfma_f32_16x16x32_bf16 v[40:43], v[178:181], v[194:197], v[40:43]
	v_mfma_f32_16x16x32_bf16 v[44:47], v[124:127], v[202:205], v[44:47]
	v_mfma_f32_16x16x32_bf16 v[48:51], v[178:181], v[202:205], v[48:51]
	v_mfma_f32_16x16x32_bf16 v[52:55], v[124:127], v[210:213], v[52:55]
	v_mfma_f32_16x16x32_bf16 v[56:59], v[178:181], v[210:213], v[56:59]
	s_setprio 0
	s_barrier
	s_mov_b32 m0, s68
	v_lshl_add_u64 v[140:141], s[8:9], 0, v[130:131]
	s_add_u32 s38, s8, 0x10000
	ds_read_b128 v[88:91], v149 offset:16384
	ds_read_b128 v[92:95], v149 offset:17408
	ds_read_b128 v[182:185], v149 offset:18432
	ds_read_b128 v[186:189], v149 offset:19456
	ds_read_b128 v[190:193], v149 offset:20480
	ds_read_b128 v[194:197], v149 offset:21504
	ds_read_b128 v[198:201], v149 offset:22528
	ds_read_b128 v[202:205], v149 offset:23552
	global_load_lds_dwordx4 v[140:141], off
	v_lshl_add_u64 v[250:251], s[8:9], 0, v[134:135]
	s_mov_b32 m0, s65
	s_addc_u32 s39, s9, 0
	global_load_lds_dwordx4 v[250:251], off
	v_lshl_add_u64 v[206:207], s[38:39], 0, v[130:131]
	s_mov_b32 m0, s66
	v_lshl_add_u64 v[252:253], s[34:35], 0, v[128:129]
	global_load_lds_dwordx4 v[206:207], off
	v_lshl_add_u64 v[206:207], s[38:39], 0, v[134:135]
	s_mov_b32 m0, s67
	v_lshl_add_u64 v[136:137], s[34:35], 0, v[132:133]
	global_load_lds_dwordx4 v[206:207], off
	s_mov_b32 m0, s55
	s_nop 0
	global_load_lds_dwordx4 v[252:253], off
	s_mov_b32 m0, s56
	s_nop 0
	global_load_lds_dwordx4 v[136:137], off
	s_waitcnt vmcnt(8)
	s_waitcnt lgkmcnt(0)
	s_barrier
	s_setprio 1
	s_waitcnt lgkmcnt(0)
	v_mfma_f32_16x16x32_bf16 v[0:3], v[104:107], v[198:201], v[0:3]
	v_mfma_f32_16x16x32_bf16 v[4:7], v[112:115], v[198:201], v[4:7]
	v_mfma_f32_16x16x32_bf16 v[150:153], v[104:107], v[88:91], v[150:153]
	v_mfma_f32_16x16x32_bf16 v[154:157], v[112:115], v[88:91], v[154:157]
	v_mfma_f32_16x16x32_bf16 v[158:161], v[104:107], v[182:185], v[158:161]
	v_mfma_f32_16x16x32_bf16 v[162:165], v[112:115], v[182:185], v[162:165]
	v_mfma_f32_16x16x32_bf16 v[166:169], v[104:107], v[190:193], v[166:169]
	v_mfma_f32_16x16x32_bf16 v[170:173], v[112:115], v[190:193], v[170:173]
	v_mfma_f32_16x16x32_bf16 v[0:3], v[108:111], v[202:205], v[0:3]
	v_mfma_f32_16x16x32_bf16 v[4:7], v[116:119], v[202:205], v[4:7]
	v_mfma_f32_16x16x32_bf16 v[150:153], v[108:111], v[92:95], v[150:153]
	v_mfma_f32_16x16x32_bf16 v[154:157], v[116:119], v[92:95], v[154:157]
	v_mfma_f32_16x16x32_bf16 v[158:161], v[108:111], v[186:189], v[158:161]
	v_mfma_f32_16x16x32_bf16 v[162:165], v[116:119], v[186:189], v[162:165]
	v_mfma_f32_16x16x32_bf16 v[166:169], v[108:111], v[194:197], v[166:169]
	v_mfma_f32_16x16x32_bf16 v[170:173], v[116:119], v[194:197], v[170:173]
	v_mfma_f32_16x16x32_bf16 v[8:11], v[120:123], v[88:91], v[8:11]
	v_mfma_f32_16x16x32_bf16 v[206:209], v[124:127], v[92:95], v[8:11]
	v_mfma_f32_16x16x32_bf16 v[8:11], v[174:177], v[88:91], v[12:15]
	v_mfma_f32_16x16x32_bf16 v[210:213], v[178:181], v[92:95], v[8:11]
	v_mfma_f32_16x16x32_bf16 v[8:11], v[120:123], v[182:185], v[24:27]
	v_mfma_f32_16x16x32_bf16 v[222:225], v[124:127], v[186:189], v[8:11]
	v_mfma_f32_16x16x32_bf16 v[8:11], v[174:177], v[182:185], v[28:31]
	v_mfma_f32_16x16x32_bf16 v[182:185], v[178:181], v[186:189], v[8:11]
	v_mfma_f32_16x16x32_bf16 v[8:11], v[120:123], v[190:193], v[60:63]
	v_mfma_f32_16x16x32_bf16 v[186:189], v[124:127], v[194:197], v[8:11]
	v_mfma_f32_16x16x32_bf16 v[8:11], v[174:177], v[190:193], v[100:103]
	v_mfma_f32_16x16x32_bf16 v[190:193], v[178:181], v[194:197], v[8:11]
	v_mfma_f32_16x16x32_bf16 v[8:11], v[120:123], v[198:201], v[16:19]
	v_mfma_f32_16x16x32_bf16 v[194:197], v[124:127], v[202:205], v[8:11]
	v_mfma_f32_16x16x32_bf16 v[8:11], v[174:177], v[198:201], v[20:23]
	v_mfma_f32_16x16x32_bf16 v[174:177], v[178:181], v[202:205], v[8:11]
	s_setprio 0
	s_barrier
; __device__ __forceinline__ int lane_id_() { int l; asm volatile("v_mbcnt_lo_u32_b32 %0, -1, 0\n\tv_mbcnt_hi_u32_b32 %0, -1, %0" : "=v"(l)); return l; }
; #define PG8_STAGE(bufoff, gbase, voff) do { _Pragma("unroll") for (int _i = 0; _i < 2; ++_i) \
;         __builtin_amdgcn_global_load_lds((const unsigned*)((const char*)(gbase) + (voff)[_i]), (LAS unsigned*)(lds + (bufoff) + ldsw + _i * 8192), 16, 0, 0); } while (0)
; #define PG8_LDA(dst, b, h) do { _Pragma("unroll") for (int m = 0; m < 4; ++m) _Pragma("unroll") for (int k = 0; k < 2; ++k) dst[m][k] = *(const LAS bf16x8*)(lds + PG8_SA(b, h) + aoff + m * 2048 + k * 1024); } while (0)
; #define PG8_LDB(dst, b, h) do { _Pragma("unroll") for (int n = 0; n < 2; ++n) _Pragma("unroll") for (int k = 0; k < 2; ++k) dst[n][k] = *(const LAS bf16x8*)(lds + PG8_SB(b, h) + boff + n * 2048 + k * 1024); } while (0)
; #define PG8_MMA(ai, bj, At, Bt) do { __builtin_amdgcn_s_setprio(1); _Pragma("unroll") for (int m = 0; m < 4; ++m) _Pragma("unroll") for (int n = 0; n < 2; ++n) _Pragma("unroll") for (int k = 0; k < 2; ++k) \
;         acc[ai][bj][m][n] = __builtin_amdgcn_mfma_f32_16x16x32_bf16(Bt[n][k], At[m][k], acc[ai][bj][m][n], 0, 0, 0); __builtin_amdgcn_s_setprio(0); } while (0)
; #define PG8_WAIT_V(n) asm volatile("s_waitcnt vmcnt(" #n ")" ::: "memory")
; #define PG8_WAIT_L(n) asm volatile("s_waitcnt lgkmcnt(" #n ")" ::: "memory")
; #define PG8_BAR __builtin_amdgcn_s_barrier()
; #define PG8_SCHED __builtin_amdgcn_sched_barrier(0)
; template <class Epi, bool ALIGN_EPI, int K, int LDA, int LDB>
; __device__ __forceinline__ void gemm_phase(LAS unsigned char* lds, const int wid, const Gemm g, const StaticOrder& S, const Epi& E) {
;     ...
;             PG8_LDB(B0, 1, 0); PG8_LDB(B1, 1, 1); PG8_SCHED; PG8_LDA(At, 1, 0); PG8_STAGE(PG8_SA(0, 1), a2 + hA, voffA);
;             PG8_WAIT_V(8); PG8_WAIT_L(0); PG8_BAR; PG8_MMA(0, 0, At, B0); PG8_MMA(0, 1, At, B1); PG8_BAR; PG8_SCHED;
;             PG8_LDA(At, 1, 1); PG8_STAGE(PG8_SB(1, 0), b3, voffB); PG8_STAGE(PG8_SB(1, 1), b3 + hB, voffB); PG8_STAGE(PG8_SA(1, 0), a3, voffA);
;             PG8_WAIT_V(8); PG8_WAIT_L(0); PG8_BAR; PG8_MMA(1, 0, At, B0); PG8_MMA(1, 1, At, B1); PG8_BAR; PG8_SCHED;
;         }
;         if constexpr (ALIGN_EPI) { if (wr == 0) PG8_BAR; }
;         { const int l2 = lane_id_(); E(acc, cur, wid >> 2, wid & 3, l2 & 15, l2 >> 4); }
;         if (!has_next) break;
	s_nop 4
	ds_read_b128 v[8:11], v142
	ds_read_b128 v[12:15], v142 offset:1024
	ds_read_b128 v[16:19], v142 offset:2048
	ds_read_b128 v[20:23], v142 offset:3072
	ds_read_b128 v[178:181], v144
	ds_read_b128 v[198:201], v144 offset:1024
	ds_read_b128 v[202:205], v144 offset:2048
	ds_read_b128 v[226:229], v144 offset:3072
	s_add_u32 s38, s34, 0xa0000
	s_addc_u32 s39, s35, 0
	s_mov_b32 m0, s57
	v_lshl_add_u64 v[88:89], s[38:39], 0, v[128:129]
	ds_read_b128 v[24:27], v149 offset:32768
	ds_read_b128 v[28:31], v149 offset:33792
	ds_read_b128 v[60:63], v149 offset:34816
	ds_read_b128 v[230:233], v149 offset:35840
	ds_read_b128 v[234:237], v149 offset:36864
	ds_read_b128 v[238:241], v149 offset:37888
	ds_read_b128 v[242:245], v149 offset:38912
	ds_read_b128 v[246:249], v149 offset:39936
	global_load_lds_dwordx4 v[88:89], off
	v_lshl_add_u64 v[88:89], s[38:39], 0, v[132:133]
	s_mov_b32 m0, s58
	s_nop 0
	global_load_lds_dwordx4 v[88:89], off
	s_waitcnt vmcnt(8)
	s_waitcnt lgkmcnt(0)
	s_barrier
	s_setprio 1
	s_waitcnt lgkmcnt(0)
	v_mfma_f32_16x16x32_bf16 v[64:67], v[8:11], v[24:27], v[64:67]
	v_mfma_f32_16x16x32_bf16 v[112:115], v[12:15], v[28:31], v[64:67]
	v_mfma_f32_16x16x32_bf16 v[64:67], v[16:19], v[24:27], v[68:71]
	v_mfma_f32_16x16x32_bf16 v[116:119], v[20:23], v[28:31], v[64:67]
	v_mfma_f32_16x16x32_bf16 v[64:67], v[8:11], v[60:63], v[72:75]
	v_mfma_f32_16x16x32_bf16 v[108:111], v[12:15], v[230:233], v[64:67]
	v_mfma_f32_16x16x32_bf16 v[64:67], v[16:19], v[60:63], v[76:79]
	v_mfma_f32_16x16x32_bf16 v[104:107], v[20:23], v[230:233], v[64:67]
	v_mfma_f32_16x16x32_bf16 v[64:67], v[8:11], v[234:237], v[80:83]
	v_mfma_f32_16x16x32_bf16 v[92:95], v[12:15], v[238:241], v[64:67]
	v_mfma_f32_16x16x32_bf16 v[64:67], v[16:19], v[234:237], v[84:87]
	v_mfma_f32_16x16x32_bf16 v[88:91], v[20:23], v[238:241], v[64:67]
	v_mfma_f32_16x16x32_bf16 v[64:67], v[8:11], v[242:245], v[214:217]
	v_mfma_f32_16x16x32_bf16 v[76:79], v[12:15], v[246:249], v[64:67]
	v_mfma_f32_16x16x32_bf16 v[64:67], v[16:19], v[242:245], v[218:221]
	v_mfma_f32_16x16x32_bf16 v[72:75], v[20:23], v[246:249], v[64:67]
	v_mfma_f32_16x16x32_bf16 v[64:67], v[178:181], v[24:27], v[96:99]
	v_mfma_f32_16x16x32_bf16 v[24:27], v[202:205], v[24:27], v[32:35]
	v_mfma_f32_16x16x32_bf16 v[124:127], v[226:229], v[28:31], v[24:27]
	v_mfma_f32_16x16x32_bf16 v[24:27], v[178:181], v[60:63], v[36:39]
	v_mfma_f32_16x16x32_bf16 v[100:103], v[198:201], v[230:233], v[24:27]
	v_mfma_f32_16x16x32_bf16 v[24:27], v[202:205], v[60:63], v[40:43]
	v_mfma_f32_16x16x32_bf16 v[96:99], v[226:229], v[230:233], v[24:27]
	v_mfma_f32_16x16x32_bf16 v[24:27], v[178:181], v[234:237], v[44:47]
	v_mfma_f32_16x16x32_bf16 v[84:87], v[198:201], v[238:241], v[24:27]
	v_mfma_f32_16x16x32_bf16 v[24:27], v[202:205], v[234:237], v[48:51]
	v_mfma_f32_16x16x32_bf16 v[80:83], v[226:229], v[238:241], v[24:27]
	v_mfma_f32_16x16x32_bf16 v[24:27], v[178:181], v[242:245], v[52:55]
	v_mfma_f32_16x16x32_bf16 v[68:71], v[198:201], v[246:249], v[24:27]
	v_mfma_f32_16x16x32_bf16 v[24:27], v[202:205], v[242:245], v[56:59]
	v_mfma_f32_16x16x32_bf16 v[120:123], v[198:201], v[28:31], v[64:67]
	v_mfma_f32_16x16x32_bf16 v[60:63], v[226:229], v[246:249], v[24:27]
	s_setprio 0
	s_barrier
	s_mov_b32 m0, s71
	s_nop 2
	v_lshl_add_u64 v[24:25], v[140:141], 0, s[14:15]
	s_add_u32 s8, s8, 0x10080
	ds_read_b128 v[32:35], v149 offset:49152
	ds_read_b128 v[36:39], v149 offset:50176
	ds_read_b128 v[214:217], v149 offset:51200
	ds_read_b128 v[218:221], v149 offset:52224
	ds_read_b128 v[230:233], v149 offset:53248
	ds_read_b128 v[234:237], v149 offset:54272
	ds_read_b128 v[238:241], v149 offset:55296
	ds_read_b128 v[242:245], v149 offset:56320
	global_load_lds_dwordx4 v[24:25], off
	v_lshl_add_u64 v[24:25], v[250:251], 0, s[14:15]
	s_mov_b32 m0, s69
	s_addc_u32 s9, s9, 0
	global_load_lds_dwordx4 v[24:25], off
	v_lshl_add_u64 v[24:25], s[8:9], 0, v[130:131]
	s_mov_b32 m0, s40
	s_nop 0
	global_load_lds_dwordx4 v[24:25], off
	v_lshl_add_u64 v[24:25], s[8:9], 0, v[134:135]
	s_mov_b32 m0, s41
	s_nop 0
	global_load_lds_dwordx4 v[24:25], off
	v_lshl_add_u64 v[24:25], v[252:253], 0, s[14:15]
	s_mov_b32 m0, s59
	s_nop 0
	global_load_lds_dwordx4 v[24:25], off
	v_lshl_add_u64 v[24:25], v[136:137], 0, s[14:15]
	s_mov_b32 m0, s60
	s_nop 0
	global_load_lds_dwordx4 v[24:25], off
	s_waitcnt vmcnt(8)
	s_waitcnt lgkmcnt(0)
	s_barrier
	s_setprio 1
	s_waitcnt lgkmcnt(0)
	v_mfma_f32_16x16x32_bf16 v[24:27], v[8:11], v[32:35], v[150:153]
	v_mfma_f32_16x16x32_bf16 v[64:67], v[12:15], v[36:39], v[24:27]
	v_mfma_f32_16x16x32_bf16 v[24:27], v[16:19], v[32:35], v[154:157]
	v_mfma_f32_16x16x32_bf16 v[56:59], v[20:23], v[36:39], v[24:27]
	v_mfma_f32_16x16x32_bf16 v[24:27], v[8:11], v[214:217], v[158:161]
	v_mfma_f32_16x16x32_bf16 v[44:47], v[12:15], v[218:221], v[24:27]
	v_mfma_f32_16x16x32_bf16 v[24:27], v[16:19], v[214:217], v[162:165]
	v_mfma_f32_16x16x32_bf16 v[40:43], v[20:23], v[218:221], v[24:27]
	v_mfma_f32_16x16x32_bf16 v[24:27], v[8:11], v[230:233], v[166:169]
	v_mfma_f32_16x16x32_bf16 v[0:3], v[8:11], v[238:241], v[0:3]
	v_mfma_f32_16x16x32_bf16 v[28:31], v[12:15], v[234:237], v[24:27]
	v_mfma_f32_16x16x32_bf16 v[24:27], v[16:19], v[230:233], v[170:173]
	v_mfma_f32_16x16x32_bf16 v[12:15], v[12:15], v[242:245], v[0:3]
	v_mfma_f32_16x16x32_bf16 v[0:3], v[16:19], v[238:241], v[4:7]
	v_mfma_f32_16x16x32_bf16 v[24:27], v[20:23], v[234:237], v[24:27]
	v_mfma_f32_16x16x32_bf16 v[8:11], v[20:23], v[242:245], v[0:3]
	v_mfma_f32_16x16x32_bf16 v[0:3], v[178:181], v[32:35], v[206:209]
	v_mfma_f32_16x16x32_bf16 v[52:55], v[198:201], v[36:39], v[0:3]
	v_mfma_f32_16x16x32_bf16 v[0:3], v[202:205], v[32:35], v[210:213]
	v_mfma_f32_16x16x32_bf16 v[48:51], v[226:229], v[36:39], v[0:3]
	v_mfma_f32_16x16x32_bf16 v[0:3], v[178:181], v[214:217], v[222:225]
	v_mfma_f32_16x16x32_bf16 v[36:39], v[198:201], v[218:221], v[0:3]
	v_mfma_f32_16x16x32_bf16 v[0:3], v[202:205], v[214:217], v[182:185]
	v_mfma_f32_16x16x32_bf16 v[32:35], v[226:229], v[218:221], v[0:3]
	v_mfma_f32_16x16x32_bf16 v[0:3], v[178:181], v[230:233], v[186:189]
	v_mfma_f32_16x16x32_bf16 v[20:23], v[198:201], v[234:237], v[0:3]
	v_mfma_f32_16x16x32_bf16 v[0:3], v[202:205], v[230:233], v[190:193]
	v_mfma_f32_16x16x32_bf16 v[16:19], v[226:229], v[234:237], v[0:3]
	v_mfma_f32_16x16x32_bf16 v[0:3], v[178:181], v[238:241], v[194:197]
	v_mfma_f32_16x16x32_bf16 v[4:7], v[198:201], v[242:245], v[0:3]
	v_mfma_f32_16x16x32_bf16 v[0:3], v[202:205], v[238:241], v[174:177]
	v_mfma_f32_16x16x32_bf16 v[0:3], v[226:229], v[242:245], v[0:3]
	s_setprio 0
	s_barrier
	s_andn2_b64 vcc, exec, s[16:17]
	s_cbranch_vccnz .LBB0_691
	s_barrier
